# EpiRes epilogue: per-load vmcnt waits in first batch and permlane16/32 swaps instead of ds_bpermute for row stats
# speedup vs baseline: 1.0064x; 1.0004x over previous
; #define PG8_STAGE(bufoff, gbase, voff) do { _Pragma("unroll") for (int _i = 0; _i < 2; ++_i) \
;     __builtin_amdgcn_global_load_lds((const unsigned*)((const char*)(gbase) + (voff)[_i]), (LAS unsigned*)(lds + (bufoff) + ldsw + _i * 8192), 16, 0, 0); } while (0)
; #define PG8_LDA(dst, b, h) do { _Pragma("unroll") for (int m = 0; m < 4; ++m) _Pragma("unroll") for (int k = 0; k < 2; ++k) dst[m][k] = *(const LAS bf16x8*)(lds + PG8_SA(b, h) + aoff + m * 2048 + k * 1024); } while (0)
; #define PG8_LDB(dst, b, h) do { _Pragma("unroll") for (int n = 0; n < 2; ++n) _Pragma("unroll") for (int k = 0; k < 2; ++k) dst[n][k] = *(const LAS bf16x8*)(lds + PG8_SB(b, h) + boff + n * 2048 + k * 1024); } while (0)
; #define PG8_WAIT_V(n) asm volatile("s_waitcnt vmcnt(" #n ")" ::: "memory")
; #define PG8_WAIT_L(n) asm volatile("s_waitcnt lgkmcnt(" #n ")" ::: "memory")
; #define PG8_BAR __builtin_amdgcn_s_barrier()
; #define PG8_SCHED __builtin_amdgcn_sched_barrier(0)
; template <class Epi>
; DI void gemm_phase(int wv, LAS unsigned char* lds, const Gemm g, const StaticOrder& S, const Epi& E) {
;     ...
;       const char* a1 = cA + (size_t)(t + 1) * kstep;
;       const char* a2 = last ? nA : cA + (size_t)(t + 2) * kstep; const char* b2 = last ? nB : cB + (size_t)(t + 2) * kstep;
;       const char* a3 = a2 + kstep; const char* b3 = b2 + kstep;
;       PG8_LDB(B0, 0, 0); PG8_SCHED; PG8_LDA(At, 0, 0); PG8_STAGE(PG8_SA(1, 1), a1 + hstep, voffA);
;       PG8_WAIT_L(8); PG8_BAR; PG8_WAIT_L(0); PG8_MMA(0, 0, At, B0); PG8_BAR; PG8_SCHED;
;       PG8_LDB(B1, 0, 1); PG8_STAGE(PG8_SB(0, 0), b2, voffA);
;       PG8_BAR; PG8_WAIT_L(0); PG8_MMA(0, 1, At, B1); PG8_BAR;
;       PG8_LDA(At, 0, 1); PG8_STAGE(PG8_SA(0, 0), a2, voffA);
;       PG8_BAR; PG8_WAIT_L(0); PG8_MMA(1, 0, At, B0); PG8_BAR; PG8_SCHED;
;       PG8_STAGE(PG8_SB(0, 1), b2 + hstep, voffA);
;       PG8_WAIT_V(6); PG8_BAR; PG8_MMA(1, 1, At, B1); PG8_BAR;
;       PG8_LDB(B0, 1, 0); PG8_SCHED; PG8_LDA(At, 1, 0); PG8_STAGE(PG8_SA(0, 1), a2 + hstep, voffA);
;       PG8_WAIT_L(8); PG8_BAR; PG8_WAIT_L(0); PG8_MMA(0, 0, At, B0); PG8_BAR; PG8_SCHED;
.LBB0_890:
	s_add_i32 vcc_hi, s34, 2
	s_add_u32 s36, s30, 0x80
	s_addc_u32 s35, s31, 0
	s_add_i32 s41, 0, 0x10000
	v_add_u32_e32 v138, s41, v246
	ds_read_b128 v[58:61], v138
	ds_read_b128 v[66:69], v138 offset:1024
	ds_read_b128 v[130:133], v138 offset:2048
	ds_read_b128 v[138:141], v138 offset:3072
	s_cmp_eq_u32 s60, s34
	s_cselect_b32 s34, s0, s36
	s_cselect_b32 s35, s1, s35
	s_cselect_b32 s37, s29, vcc_lo
	s_cselect_b32 s36, s28, s95
	v_lshl_add_u64 v[178:179], s[30:31], 0, v[206:207]
	s_add_i32 m0, s62, 0xc000
	ds_read_b128 v[142:145], v248
	ds_read_b128 v[146:149], v248 offset:1024
	ds_read_b128 v[150:153], v248 offset:2048
	ds_read_b128 v[154:157], v248 offset:3072
	ds_read_b128 v[158:161], v248 offset:4096
	ds_read_b128 v[166:169], v248 offset:5120
	ds_read_b128 v[170:173], v248 offset:6144
	ds_read_b128 v[174:177], v248 offset:7168
	global_load_lds_dwordx4 v[178:179], off
	v_lshl_add_u64 v[178:179], s[30:31], 0, v[208:209]
	s_add_i32 m0, s62, 0xe000
	s_nop 0
	global_load_lds_dwordx4 v[178:179], off
	s_waitcnt lgkmcnt(8)
	s_barrier
	s_waitcnt lgkmcnt(0)
	s_setprio 1
	s_waitcnt lgkmcnt(0)
	v_mfma_f32_16x16x32_f16 v[162:165], v[58:61], v[142:145], v[162:165]
	v_mfma_f32_16x16x32_f16 v[134:137], v[130:133], v[142:145], v[134:137]
	v_mfma_f32_16x16x32_f16 v[118:121], v[58:61], v[150:153], v[118:121]
	v_mfma_f32_16x16x32_f16 v[114:117], v[130:133], v[150:153], v[114:117]
	v_mfma_f32_16x16x32_f16 v[102:105], v[58:61], v[158:161], v[102:105]
	v_mfma_f32_16x16x32_f16 v[98:101], v[130:133], v[158:161], v[98:101]
	v_mfma_f32_16x16x32_f16 v[86:89], v[58:61], v[170:173], v[86:89]
	v_mfma_f32_16x16x32_f16 v[82:85], v[130:133], v[170:173], v[82:85]
	v_mfma_f32_16x16x32_f16 v[162:165], v[66:69], v[146:149], v[162:165]
	v_mfma_f32_16x16x32_f16 v[134:137], v[138:141], v[146:149], v[134:137]
	v_mfma_f32_16x16x32_f16 v[118:121], v[66:69], v[154:157], v[118:121]
	v_mfma_f32_16x16x32_f16 v[114:117], v[138:141], v[154:157], v[114:117]
	v_mfma_f32_16x16x32_f16 v[102:105], v[66:69], v[166:169], v[102:105]
	v_mfma_f32_16x16x32_f16 v[98:101], v[138:141], v[166:169], v[98:101]
	v_mfma_f32_16x16x32_f16 v[86:89], v[66:69], v[174:177], v[86:89]
	v_mfma_f32_16x16x32_f16 v[82:85], v[138:141], v[174:177], v[82:85]
	s_setprio 0
	s_barrier
	s_add_i32 s42, 0, 0x14000
	s_add_i32 s41, s41, s57
	v_add_u32_e32 v190, s42, v246
	v_lshl_add_u64 v[210:211], s[36:37], 0, v[202:203]
	s_mov_b32 m0, s41
	ds_read_b128 v[178:181], v190
	ds_read_b128 v[182:185], v190 offset:1024
	ds_read_b128 v[186:189], v190 offset:2048
	ds_read_b128 v[190:193], v190 offset:3072
	global_load_lds_dwordx4 v[210:211], off
	v_lshl_add_u64 v[212:213], s[36:37], 0, v[204:205]
	s_add_i32 m0, s41, 0x2000
	s_nop 0
	global_load_lds_dwordx4 v[212:213], off
	s_barrier
	s_waitcnt lgkmcnt(0)
	s_setprio 1
	s_waitcnt lgkmcnt(0)
	v_mfma_f32_16x16x32_f16 v[126:129], v[178:181], v[142:145], v[126:129]
	v_mfma_f32_16x16x32_f16 v[122:125], v[186:189], v[142:145], v[122:125]
	v_mfma_f32_16x16x32_f16 v[110:113], v[178:181], v[150:153], v[110:113]
	v_mfma_f32_16x16x32_f16 v[106:109], v[186:189], v[150:153], v[106:109]
	v_mfma_f32_16x16x32_f16 v[94:97], v[178:181], v[158:161], v[94:97]
	v_mfma_f32_16x16x32_f16 v[90:93], v[186:189], v[158:161], v[90:93]
	v_mfma_f32_16x16x32_f16 v[78:81], v[178:181], v[170:173], v[78:81]
	v_mfma_f32_16x16x32_f16 v[74:77], v[186:189], v[170:173], v[74:77]
	v_mfma_f32_16x16x32_f16 v[126:129], v[182:185], v[146:149], v[126:129]
	v_mfma_f32_16x16x32_f16 v[122:125], v[190:193], v[146:149], v[122:125]
	v_mfma_f32_16x16x32_f16 v[110:113], v[182:185], v[154:157], v[110:113]
	v_mfma_f32_16x16x32_f16 v[106:109], v[190:193], v[154:157], v[106:109]
	v_mfma_f32_16x16x32_f16 v[94:97], v[182:185], v[166:169], v[94:97]
	v_mfma_f32_16x16x32_f16 v[90:93], v[190:193], v[166:169], v[90:93]
	v_mfma_f32_16x16x32_f16 v[78:81], v[182:185], v[174:177], v[78:81]
	v_mfma_f32_16x16x32_f16 v[74:77], v[190:193], v[174:177], v[74:77]
	s_setprio 0
	s_mov_b32 m0, s62
	v_lshl_add_u64 v[214:215], s[34:35], 0, v[202:203]
	s_barrier
	ds_read_b128 v[142:145], v248 offset:16384
	ds_read_b128 v[146:149], v248 offset:17408
	ds_read_b128 v[150:153], v248 offset:18432
	ds_read_b128 v[154:157], v248 offset:19456
	ds_read_b128 v[158:161], v248 offset:20480
	ds_read_b128 v[166:169], v248 offset:21504
	ds_read_b128 v[170:173], v248 offset:22528
	ds_read_b128 v[174:177], v248 offset:23552
	global_load_lds_dwordx4 v[214:215], off
	v_lshl_add_u64 v[216:217], s[34:35], 0, v[204:205]
	s_mov_b32 m0, s64
	s_nop 0
	global_load_lds_dwordx4 v[216:217], off
	s_barrier
	s_waitcnt lgkmcnt(0)
	s_setprio 1
	s_waitcnt lgkmcnt(0)
	v_mfma_f32_16x16x32_f16 v[70:73], v[58:61], v[142:145], v[70:73]
	v_mfma_f32_16x16x32_f16 v[62:65], v[130:133], v[142:145], v[62:65]
	v_mfma_f32_16x16x32_f16 v[46:49], v[58:61], v[150:153], v[46:49]
	v_mfma_f32_16x16x32_f16 v[42:45], v[130:133], v[150:153], v[42:45]
	v_mfma_f32_16x16x32_f16 v[28:31], v[58:61], v[158:161], v[28:31]
	v_mfma_f32_16x16x32_f16 v[24:27], v[130:133], v[158:161], v[24:27]
	v_mfma_f32_16x16x32_f16 v[12:15], v[58:61], v[170:173], v[12:15]
	v_mfma_f32_16x16x32_f16 v[8:11], v[130:133], v[170:173], v[8:11]
	v_mfma_f32_16x16x32_f16 v[70:73], v[66:69], v[146:149], v[70:73]
	v_mfma_f32_16x16x32_f16 v[62:65], v[138:141], v[146:149], v[62:65]
	v_mfma_f32_16x16x32_f16 v[46:49], v[66:69], v[154:157], v[46:49]
	v_mfma_f32_16x16x32_f16 v[42:45], v[138:141], v[154:157], v[42:45]
	v_mfma_f32_16x16x32_f16 v[28:31], v[66:69], v[166:169], v[28:31]
	v_mfma_f32_16x16x32_f16 v[24:27], v[138:141], v[166:169], v[24:27]
	v_mfma_f32_16x16x32_f16 v[12:15], v[66:69], v[174:177], v[12:15]
	v_mfma_f32_16x16x32_f16 v[8:11], v[138:141], v[174:177], v[8:11]
	s_setprio 0
	s_barrier
; #define PG8_STAGE(bufoff, gbase, voff) do { _Pragma("unroll") for (int _i = 0; _i < 2; ++_i) \
;     __builtin_amdgcn_global_load_lds((const unsigned*)((const char*)(gbase) + (voff)[_i]), (LAS unsigned*)(lds + (bufoff) + ldsw + _i * 8192), 16, 0, 0); } while (0)
; #define PG8_LDA(dst, b, h) do { _Pragma("unroll") for (int m = 0; m < 4; ++m) _Pragma("unroll") for (int k = 0; k < 2; ++k) dst[m][k] = *(const LAS bf16x8*)(lds + PG8_SA(b, h) + aoff + m * 2048 + k * 1024); } while (0)
; #define PG8_LDB(dst, b, h) do { _Pragma("unroll") for (int n = 0; n < 2; ++n) _Pragma("unroll") for (int k = 0; k < 2; ++k) dst[n][k] = *(const LAS bf16x8*)(lds + PG8_SB(b, h) + boff + n * 2048 + k * 1024); } while (0)
; #define PG8_WAIT_V(n) asm volatile("s_waitcnt vmcnt(" #n ")" ::: "memory")
; #define PG8_WAIT_L(n) asm volatile("s_waitcnt lgkmcnt(" #n ")" ::: "memory")
; #define PG8_BAR __builtin_amdgcn_s_barrier()
; #define PG8_SCHED __builtin_amdgcn_sched_barrier(0)
; template <class Epi>
; DI void gemm_phase(int wv, LAS unsigned char* lds, const Gemm g, const StaticOrder& S, const Epi& E) {
;     ...
;       PG8_STAGE(PG8_SB(0, 1), b2 + hstep, voffA);
;       PG8_WAIT_V(6); PG8_BAR; PG8_MMA(1, 1, At, B1); PG8_BAR;
;       PG8_LDB(B0, 1, 0); PG8_SCHED; PG8_LDA(At, 1, 0); PG8_STAGE(PG8_SA(0, 1), a2 + hstep, voffA);
;       PG8_WAIT_L(8); PG8_BAR; PG8_WAIT_L(0); PG8_MMA(0, 0, At, B0); PG8_BAR; PG8_SCHED;
;       PG8_LDB(B1, 1, 1); PG8_STAGE(PG8_SB(1, 0), b3, voffA);
;       PG8_BAR; PG8_WAIT_L(0); PG8_MMA(0, 1, At, B1); PG8_BAR;
;       PG8_LDA(At, 1, 1); PG8_STAGE(PG8_SA(1, 0), a3, voffA);
;       PG8_BAR; PG8_WAIT_L(0); PG8_MMA(1, 0, At, B0); PG8_BAR; PG8_SCHED;
;       PG8_STAGE(PG8_SB(1, 1), b3 + hstep, voffA);
;       PG8_WAIT_V(6); PG8_BAR; PG8_MMA(1, 1, At, B1); PG8_BAR;
	s_add_u32 s36, s36, s84
	s_addc_u32 s37, s37, 0
	s_add_i32 s41, s42, s57
	v_lshl_add_u64 v[218:219], s[36:37], 0, v[202:203]
	s_mov_b32 m0, s41
	v_lshl_add_u64 v[220:221], s[36:37], 0, v[204:205]
	global_load_lds_dwordx4 v[218:219], off
	s_add_i32 m0, s41, 0x2000
	s_nop 0
	global_load_lds_dwordx4 v[220:221], off
	s_waitcnt vmcnt(6)
	s_barrier
	s_setprio 1
	v_mfma_f32_16x16x32_f16 v[54:57], v[178:181], v[142:145], v[54:57]
	v_mfma_f32_16x16x32_f16 v[50:53], v[186:189], v[142:145], v[50:53]
	v_mfma_f32_16x16x32_f16 v[38:41], v[178:181], v[150:153], v[38:41]
	v_mfma_f32_16x16x32_f16 v[34:37], v[186:189], v[150:153], v[34:37]
	v_mfma_f32_16x16x32_f16 v[20:23], v[178:181], v[158:161], v[20:23]
	v_mfma_f32_16x16x32_f16 v[16:19], v[186:189], v[158:161], v[16:19]
	v_mfma_f32_16x16x32_f16 v[4:7], v[178:181], v[170:173], v[4:7]
	v_mfma_f32_16x16x32_f16 v[0:3], v[186:189], v[170:173], v[0:3]
	v_mfma_f32_16x16x32_f16 v[54:57], v[182:185], v[146:149], v[54:57]
	v_mfma_f32_16x16x32_f16 v[50:53], v[190:193], v[146:149], v[50:53]
	v_mfma_f32_16x16x32_f16 v[38:41], v[182:185], v[154:157], v[38:41]
	v_mfma_f32_16x16x32_f16 v[34:37], v[190:193], v[154:157], v[34:37]
	v_mfma_f32_16x16x32_f16 v[20:23], v[182:185], v[166:169], v[20:23]
	v_mfma_f32_16x16x32_f16 v[16:19], v[190:193], v[166:169], v[16:19]
	v_mfma_f32_16x16x32_f16 v[4:7], v[182:185], v[174:177], v[4:7]
	v_mfma_f32_16x16x32_f16 v[0:3], v[190:193], v[174:177], v[0:3]
	s_setprio 0
	s_add_i32 s36, 0, 0x18000
	v_add_u32_e32 v138, s36, v246
	s_barrier
	ds_read_b128 v[58:61], v138
	ds_read_b128 v[66:69], v138 offset:1024
	ds_read_b128 v[130:133], v138 offset:2048
	ds_read_b128 v[138:141], v138 offset:3072
	s_add_u32 s34, s34, s84
	s_addc_u32 s35, s35, 0
	s_mov_b32 m0, s65
	v_lshl_add_u64 v[178:179], s[34:35], 0, v[202:203]
	ds_read_b128 v[142:145], v248 offset:32768
	ds_read_b128 v[146:149], v248 offset:33792
	ds_read_b128 v[150:153], v248 offset:34816
	ds_read_b128 v[154:157], v248 offset:35840
	ds_read_b128 v[158:161], v248 offset:36864
	ds_read_b128 v[166:169], v248 offset:37888
	ds_read_b128 v[170:173], v248 offset:38912
	ds_read_b128 v[174:177], v248 offset:39936
	global_load_lds_dwordx4 v[178:179], off
	v_lshl_add_u64 v[178:179], s[34:35], 0, v[204:205]
	s_mov_b32 m0, s70
	s_nop 0
	global_load_lds_dwordx4 v[178:179], off
	s_waitcnt lgkmcnt(8)
	s_barrier
	s_waitcnt lgkmcnt(0)
	s_setprio 1
	s_waitcnt lgkmcnt(0)
	v_mfma_f32_16x16x32_f16 v[162:165], v[58:61], v[142:145], v[162:165]
	v_mfma_f32_16x16x32_f16 v[134:137], v[130:133], v[142:145], v[134:137]
	v_mfma_f32_16x16x32_f16 v[118:121], v[58:61], v[150:153], v[118:121]
	v_mfma_f32_16x16x32_f16 v[114:117], v[130:133], v[150:153], v[114:117]
	v_mfma_f32_16x16x32_f16 v[102:105], v[58:61], v[158:161], v[102:105]
	v_mfma_f32_16x16x32_f16 v[98:101], v[130:133], v[158:161], v[98:101]
	v_mfma_f32_16x16x32_f16 v[86:89], v[58:61], v[170:173], v[86:89]
	v_mfma_f32_16x16x32_f16 v[82:85], v[130:133], v[170:173], v[82:85]
	v_mfma_f32_16x16x32_f16 v[162:165], v[66:69], v[146:149], v[162:165]
	v_mfma_f32_16x16x32_f16 v[134:137], v[138:141], v[146:149], v[134:137]
	v_mfma_f32_16x16x32_f16 v[118:121], v[66:69], v[154:157], v[118:121]
	v_mfma_f32_16x16x32_f16 v[114:117], v[138:141], v[154:157], v[114:117]
	v_mfma_f32_16x16x32_f16 v[102:105], v[66:69], v[166:169], v[102:105]
	v_mfma_f32_16x16x32_f16 v[98:101], v[138:141], v[166:169], v[98:101]
	v_mfma_f32_16x16x32_f16 v[86:89], v[66:69], v[174:177], v[86:89]
	v_mfma_f32_16x16x32_f16 v[82:85], v[138:141], v[174:177], v[82:85]
	s_setprio 0
	s_barrier
	s_add_i32 s34, 0, 0x1c000
	s_add_i32 s35, s36, s57
	v_add_u32_e32 v190, s34, v246
	v_lshl_add_u64 v[210:211], v[210:211], 0, s[2:3]
	s_mov_b32 m0, s35
	ds_read_b128 v[178:181], v190
	ds_read_b128 v[182:185], v190 offset:1024
	ds_read_b128 v[186:189], v190 offset:2048
	ds_read_b128 v[190:193], v190 offset:3072
	global_load_lds_dwordx4 v[210:211], off
	v_lshl_add_u64 v[210:211], v[212:213], 0, s[2:3]
	s_add_i32 m0, s35, 0x2000
	s_nop 0
	global_load_lds_dwordx4 v[210:211], off
	s_barrier
	s_waitcnt lgkmcnt(0)
	s_setprio 1
	s_waitcnt lgkmcnt(0)
	v_mfma_f32_16x16x32_f16 v[126:129], v[178:181], v[142:145], v[126:129]
	v_mfma_f32_16x16x32_f16 v[122:125], v[186:189], v[142:145], v[122:125]
	v_mfma_f32_16x16x32_f16 v[110:113], v[178:181], v[150:153], v[110:113]
	v_mfma_f32_16x16x32_f16 v[106:109], v[186:189], v[150:153], v[106:109]
	v_mfma_f32_16x16x32_f16 v[94:97], v[178:181], v[158:161], v[94:97]
	v_mfma_f32_16x16x32_f16 v[90:93], v[186:189], v[158:161], v[90:93]
	v_mfma_f32_16x16x32_f16 v[78:81], v[178:181], v[170:173], v[78:81]
	v_mfma_f32_16x16x32_f16 v[74:77], v[186:189], v[170:173], v[74:77]
	v_mfma_f32_16x16x32_f16 v[126:129], v[182:185], v[146:149], v[126:129]
	v_mfma_f32_16x16x32_f16 v[122:125], v[190:193], v[146:149], v[122:125]
	v_mfma_f32_16x16x32_f16 v[110:113], v[182:185], v[154:157], v[110:113]
	v_mfma_f32_16x16x32_f16 v[106:109], v[190:193], v[154:157], v[106:109]
	v_mfma_f32_16x16x32_f16 v[94:97], v[182:185], v[166:169], v[94:97]
	v_mfma_f32_16x16x32_f16 v[90:93], v[190:193], v[166:169], v[90:93]
	v_mfma_f32_16x16x32_f16 v[78:81], v[182:185], v[174:177], v[78:81]
	v_mfma_f32_16x16x32_f16 v[74:77], v[190:193], v[174:177], v[74:77]
	s_setprio 0
	s_mov_b32 m0, s71
	v_lshl_add_u64 v[210:211], v[214:215], 0, s[2:3]
	s_barrier
	ds_read_b128 v[142:145], v248 offset:49152
	ds_read_b128 v[146:149], v248 offset:50176
	ds_read_b128 v[150:153], v248 offset:51200
	ds_read_b128 v[154:157], v248 offset:52224
	ds_read_b128 v[158:161], v248 offset:53248
	ds_read_b128 v[166:169], v248 offset:54272
	ds_read_b128 v[170:173], v248 offset:55296
	ds_read_b128 v[174:177], v248 offset:56320
	global_load_lds_dwordx4 v[210:211], off
	v_lshl_add_u64 v[210:211], v[216:217], 0, s[2:3]
	s_mov_b32 m0, s82
	s_nop 0
	global_load_lds_dwordx4 v[210:211], off
	s_barrier
; #define LAS __attribute__((address_space(3)))
; #define PG8_STAGE(bufoff, gbase, voff) do { _Pragma("unroll") for (int _i = 0; _i < 2; ++_i) \
;     __builtin_amdgcn_global_load_lds((const unsigned*)((const char*)(gbase) + (voff)[_i]), (LAS unsigned*)(lds + (bufoff) + ldsw + _i * 8192), 16, 0, 0); } while (0)
; template <class Epi>
; DI void gemm_phase(int wv, LAS unsigned char* lds, const Gemm g, const StaticOrder& S, const Epi& E) {
;     ...
;       PG8_BAR; PG8_WAIT_L(0); PG8_MMA(1, 0, At, B0); PG8_BAR; PG8_SCHED;
;       PG8_STAGE(PG8_SB(1, 1), b3 + hstep, voffA);
;       PG8_WAIT_V(6); PG8_BAR; PG8_MMA(1, 1, At, B1); PG8_BAR;
;   DI void operator()(const f32x4 (&acc)[2][2][4][2], const pg8::Unit& u, int wr, int wc, int fr, int fq, LAS unsigned char* lds, int ui, int wid) const {
;     const int col0 = u.pn * 256 + wc * 32 + 8 * fq;
;     int fq_ = fq, fr_ = fr; asm volatile("" : "+v"(fq_), "+v"(fr_));
;     const LAS float* gl = (const LAS float*)(lds + 139264 + (ui & 1) * 3072) + wc * 32 + 8 * fq_;
;     const LAS float* sl = (const LAS float*)(lds + 131072 + wid * 1024);
;     float rmu[8], rrs[8];
; #pragma unroll
;     for (int i = 0; i < 8; ++i) { typedef float f32x2_ __attribute__((ext_vector_type(2))); const f32x2_ sv = *(const LAS f32x2_*)(sl + (i >> 2) * 128 + ((i & 3) * 16 + fr_) * 2);
;       const float mu = sv.x * (1.0f / 1024.0f), var = fmaxf(sv.y * (1.0f / 1024.0f) - mu * mu, 0.f); rmu[i] = mu; rrs[i] = rsqrtf(var + 1e-5f); }
; #pragma unroll
;     for (int ai = 0; ai < 2; ++ai) {
;       half8 tpv[4][2];
; #pragma unroll
;       for (int m = 0; m < 4; ++m)
; #pragma unroll
;         for (int bj = 0; bj < 2; ++bj) tpv[m][bj] = *(const half8*)(tb + (size_t)(u.pm * 256 + ai * 128 + wr * 64 + m * 16 + fr) * DM + col0 + bj * 128);
; #pragma unroll
;       for (int m = 0; m < 4; ++m) {
;         const int row = u.pm * 256 + ai * 128 + wr * 64 + m * 16 + fr; const float mu = rmu[ai * 4 + m], rstd = rrs[ai * 4 + m];
;         float rs = 0.f, rq = 0.f;
; #pragma unroll
;         for (int bj = 0; bj < 2; ++bj) {
;           u32x4 w;
; #pragma unroll
;           for (int n = 0; n < 2; ++n) {
;             f32x4 tp;
; #pragma unroll
;             for (int j = 0; j < 4; ++j) tp[j] = (float)tpv[m][bj][4 * n + j];
;             tp = (tp - mu) * rstd * (*(const LAS f32x4*)(gl + bj * 128 + 4 * n)) + *(const LAS f32x4*)(gl + 256 + bj * 128 + 4 * n);
	s_waitcnt lgkmcnt(0)
	s_setprio 1
	s_waitcnt lgkmcnt(0)
	v_mfma_f32_16x16x32_f16 v[70:73], v[58:61], v[142:145], v[70:73]
	v_mfma_f32_16x16x32_f16 v[62:65], v[130:133], v[142:145], v[62:65]
	v_mfma_f32_16x16x32_f16 v[46:49], v[58:61], v[150:153], v[46:49]
	v_mfma_f32_16x16x32_f16 v[42:45], v[130:133], v[150:153], v[42:45]
	v_mfma_f32_16x16x32_f16 v[28:31], v[58:61], v[158:161], v[28:31]
	v_mfma_f32_16x16x32_f16 v[24:27], v[130:133], v[158:161], v[24:27]
	v_mfma_f32_16x16x32_f16 v[12:15], v[58:61], v[170:173], v[12:15]
	v_mfma_f32_16x16x32_f16 v[8:11], v[130:133], v[170:173], v[8:11]
	v_mfma_f32_16x16x32_f16 v[70:73], v[66:69], v[146:149], v[70:73]
	v_mfma_f32_16x16x32_f16 v[62:65], v[138:141], v[146:149], v[62:65]
	v_mfma_f32_16x16x32_f16 v[46:49], v[66:69], v[154:157], v[46:49]
	v_mfma_f32_16x16x32_f16 v[42:45], v[138:141], v[154:157], v[42:45]
	v_mfma_f32_16x16x32_f16 v[28:31], v[66:69], v[166:169], v[28:31]
	v_mfma_f32_16x16x32_f16 v[24:27], v[138:141], v[166:169], v[24:27]
	v_mfma_f32_16x16x32_f16 v[12:15], v[66:69], v[174:177], v[12:15]
	v_mfma_f32_16x16x32_f16 v[8:11], v[138:141], v[174:177], v[8:11]
	s_setprio 0
	s_barrier
	s_add_i32 s34, s34, s57
	v_lshl_add_u64 v[58:59], v[218:219], 0, s[2:3]
	s_mov_b32 m0, s34
	s_nop 0
	global_load_lds_dwordx4 v[58:59], off
	v_lshl_add_u64 v[58:59], v[220:221], 0, s[2:3]
	s_add_i32 m0, s34, 0x2000
	s_nop 0
	global_load_lds_dwordx4 v[58:59], off
	s_waitcnt vmcnt(6)
	s_barrier
	s_setprio 1
	v_mfma_f32_16x16x32_f16 v[54:57], v[178:181], v[142:145], v[54:57]
	v_mfma_f32_16x16x32_f16 v[50:53], v[186:189], v[142:145], v[50:53]
	v_mfma_f32_16x16x32_f16 v[38:41], v[178:181], v[150:153], v[38:41]
	v_mfma_f32_16x16x32_f16 v[34:37], v[186:189], v[150:153], v[34:37]
	v_mfma_f32_16x16x32_f16 v[20:23], v[178:181], v[158:161], v[20:23]
	v_mfma_f32_16x16x32_f16 v[16:19], v[186:189], v[158:161], v[16:19]
	v_mfma_f32_16x16x32_f16 v[4:7], v[178:181], v[170:173], v[4:7]
	v_mfma_f32_16x16x32_f16 v[0:3], v[186:189], v[170:173], v[0:3]
	v_mfma_f32_16x16x32_f16 v[54:57], v[182:185], v[146:149], v[54:57]
	v_mfma_f32_16x16x32_f16 v[50:53], v[190:193], v[146:149], v[50:53]
	v_mfma_f32_16x16x32_f16 v[38:41], v[182:185], v[154:157], v[38:41]
	v_mfma_f32_16x16x32_f16 v[34:37], v[190:193], v[154:157], v[34:37]
	v_mfma_f32_16x16x32_f16 v[20:23], v[182:185], v[166:169], v[20:23]
	v_mfma_f32_16x16x32_f16 v[16:19], v[190:193], v[166:169], v[16:19]
	v_mfma_f32_16x16x32_f16 v[4:7], v[182:185], v[174:177], v[4:7]
	v_mfma_f32_16x16x32_f16 v[0:3], v[190:193], v[174:177], v[0:3]
	s_setprio 0
	s_add_u32 s30, s30, 0x100
	s_addc_u32 s31, s31, 0
	s_add_u32 s95, s95, 0x100
	s_addc_u32 vcc_lo, vcc_lo, 0
	s_cmp_ge_u32 vcc_hi, s51
	s_mov_b32 s34, vcc_hi
	s_barrier
	s_cbranch_scc0 .LBB0_890
	v_mov_b32_e32 v58, v243
	v_mov_b32_e32 v59, v244
	s_mov_b32 s36, 0x800000
	v_lshlrev_b32_e32 v138, 5, v58
	v_lshl_add_u32 v58, v59, 3, s63
	ds_read2_b64 v[168:171], v58 offset1:16
	s_bitcmp1_b32 s94, 0
	v_lshl_add_u32 v212, s78, 8, v245
	s_cselect_b32 s30, 0xc00, 0
	v_or_b32_e32 v220, 32, v212
	s_waitcnt lgkmcnt(0)
	v_pk_mul_f32 v[192:193], v[168:169], s[44:45] op_sel_hi:[1,0]
	s_add_i32 s30, s86, s30
	v_fma_f32 v59, -v192, v192, v193
	v_max_f32_e32 v59, 0, v59
	v_add_f32_e32 v59, 0x3727c5ac, v59
	v_cmp_gt_f32_e32 vcc, s36, v59
	v_mul_f32_e32 v60, 0x4b800000, v59
	v_ashrrev_i32_e32 v221, 31, v220
	v_cndmask_b32_e32 v59, v59, v60, vcc
	v_rsq_f32_e32 v59, v59
	v_and_b32_e32 v139, 64, v240
	v_lshlrev_b64 v[222:223], 11, v[220:221]
	v_add_u32_e32 v221, s30, v138
	v_mul_f32_e32 v60, 0x45800000, v59
	v_xor_b32_e32 v138, 16, v240
	v_add_u32_e32 v139, 64, v139
	v_or_b32_e32 v214, 48, v212
	v_cndmask_b32_e32 v228, v59, v60, vcc
	v_cmp_lt_i32_e32 vcc, v138, v139
	v_lshl_or_b32 v210, s79, 8, v247
	v_ashrrev_i32_e32 v215, 31, v214
	v_cndmask_b32_e32 v138, v240, v138, vcc
	v_ashrrev_i32_e32 v211, 31, v210
	v_lshlrev_b64 v[218:219], 11, v[214:215]
	v_lshlrev_b32_e32 v215, 2, v138
	v_xor_b32_e32 v138, 32, v240
	v_ashrrev_i32_e32 v213, 31, v212
	v_cmp_lt_i32_e32 vcc, v138, v139
	v_lshlrev_b64 v[190:191], 1, v[210:211]
	v_lshlrev_b64 v[184:185], 11, v[212:213]
	v_cndmask_b32_e32 v138, v240, v138, vcc
	v_lshl_add_u64 v[216:217], s[76:77], 0, v[190:191]
	v_lshlrev_b32_e32 v213, 2, v138
	v_lshl_add_u64 v[138:139], v[216:217], 0, v[184:185]
	ds_read2_b64 v[130:133], v58 offset0:32 offset1:48
	ds_read2_b64 v[66:69], v58 offset0:64 offset1:80
	ds_read2_b64 v[58:61], v58 offset0:96 offset1:112
	global_load_dwordx4 v[180:183], v[138:139], off
	global_load_dwordx4 v[186:189], v[138:139], off offset:256
	v_or_b32_e32 v224, 16, v212
	v_ashrrev_i32_e32 v225, 31, v224
	v_lshlrev_b64 v[226:227], 11, v[224:225]
	v_lshl_add_u64 v[138:139], v[216:217], 0, v[226:227]
	global_load_dwordx4 v[176:179], v[138:139], off
	global_load_dwordx4 v[172:175], v[138:139], off offset:256
	v_lshl_add_u64 v[138:139], v[216:217], 0, v[222:223]
	global_load_dwordx4 v[166:169], v[138:139], off
	global_load_dwordx4 v[158:161], v[138:139], off offset:256
	v_lshl_add_u64 v[138:139], v[216:217], 0, v[218:219]
	global_load_dwordx4 v[142:145], v[138:139], off
	s_nop 0
	global_load_dwordx4 v[138:141], v[138:139], off offset:256
	s_waitcnt vmcnt(7)
	v_cvt_f32_f16_sdwa v149, v180 dst_sel:DWORD dst_unused:UNUSED_PAD src0_sel:WORD_1
	v_cvt_f32_f16_e32 v148, v180
	v_cvt_f32_f16_sdwa v147, v181 dst_sel:DWORD dst_unused:UNUSED_PAD src0_sel:WORD_1
	v_cvt_f32_f16_e32 v146, v181
	v_sub_f32_e32 v149, v149, v192
	v_sub_f32_e32 v148, v148, v192
	v_sub_f32_e32 v147, v147, v192
	v_sub_f32_e32 v146, v146, v192
	v_pk_mul_f32 v[180:181], v[228:229], v[148:149] op_sel_hi:[0,1]
	v_pk_mul_f32 v[230:231], v[228:229], v[146:147] op_sel_hi:[0,1]
	ds_read_b128 v[150:153], v221
	ds_read_b128 v[146:149], v221 offset:16
	ds_read_b128 v[154:157], v221 offset:1024
	s_waitcnt lgkmcnt(0)
; #define LAS __attribute__((address_space(3)))
; DI unsigned pkh2(float a, float b) { typedef _Float16 h2 __attribute__((ext_vector_type(2))); h2 v; v[0] = (_Float16)a; v[1] = (_Float16)b; return __builtin_bit_cast(unsigned, v); }
;   DI void operator()(const f32x4 (&acc)[2][2][4][2], const pg8::Unit& u, int wr, int wc, int fr, int fq, LAS unsigned char* lds, int ui, int wid) const {
;     ...
;       for (int m = 0; m < 4; ++m) {
;         const int row = u.pm * 256 + ai * 128 + wr * 64 + m * 16 + fr; const float mu = rmu[ai * 4 + m], rstd = rrs[ai * 4 + m];
;         float rs = 0.f, rq = 0.f;
; #pragma unroll
;         for (int bj = 0; bj < 2; ++bj) {
;           u32x4 w;
; #pragma unroll
;           for (int n = 0; n < 2; ++n) {
;             f32x4 tp;
; #pragma unroll
;             for (int j = 0; j < 4; ++j) tp[j] = (float)tpv[m][bj][4 * n + j];
;             tp = (tp - mu) * rstd * (*(const LAS f32x4*)(gl + bj * 128 + 4 * n)) + *(const LAS f32x4*)(gl + 256 + bj * 128 + 4 * n);
;             const f32x4 tn = tp * ALPHA + acc[ai][bj][m][n] * scale;
;             w[2 * n] = pkh2(tn[0], tn[1]); w[2 * n + 1] = pkh2(tn[2], tn[3]);
;             rs += tn[0] + tn[1] + tn[2] + tn[3]; rq += tn[0] * tn[0] + tn[1] * tn[1] + tn[2] * tn[2] + tn[3] * tn[3];
;           }
;           *(u32x4*)(tb + (size_t)row * DM + col0 + bj * 128) = w;
;         }
;         rs += __shfl_xor(rs, 16); rs += __shfl_xor(rs, 32); rq += __shfl_xor(rq, 16); rq += __shfl_xor(rq, 32);
;         if (fq == 0) { atomicAdd(stats_new + 2 * row, rs); atomicAdd(stats_new + 2 * row + 1, rq); }
	v_pk_fma_f32 v[180:181], v[180:181], v[150:151], v[154:155]
	s_nop 0
	v_pk_mul_f32 v[180:181], v[180:181], s[52:53] op_sel_hi:[1,0]
	v_pk_fma_f32 v[230:231], v[230:231], v[152:153], v[156:157]
	v_pk_fma_f32 v[162:163], s[12:13], v[162:163], v[180:181]
	v_pk_mul_f32 v[230:231], v[230:231], s[52:53] op_sel_hi:[1,0]
	v_mul_f32_e32 v225, v163, v163
	v_pk_fma_f32 v[164:165], s[14:15], v[164:165], v[230:231]
	v_add_f32_e32 v193, v162, v163
	v_fmac_f32_e32 v225, v162, v162
	v_add_f32_e32 v193, v164, v193
	v_fmac_f32_e32 v225, v164, v164
	v_cvt_pk_f16_f32 v180, v162, v163
	v_cvt_pk_f16_f32 v181, v164, v165
	v_add_f32_e32 v193, v165, v193
	v_fmac_f32_e32 v225, v165, v165
	v_cvt_f32_f16_sdwa v165, v182 dst_sel:DWORD dst_unused:UNUSED_PAD src0_sel:WORD_1
	v_cvt_f32_f16_e32 v164, v182
	v_cvt_f32_f16_sdwa v163, v183 dst_sel:DWORD dst_unused:UNUSED_PAD src0_sel:WORD_1
	v_cvt_f32_f16_e32 v162, v183
	v_sub_f32_e32 v165, v165, v192
	v_sub_f32_e32 v164, v164, v192
	v_sub_f32_e32 v163, v163, v192
	v_sub_f32_e32 v162, v162, v192
	v_pk_mul_f32 v[182:183], v[228:229], v[164:165] op_sel_hi:[0,1]
	v_pk_mul_f32 v[230:231], v[228:229], v[162:163] op_sel_hi:[0,1]
	ds_read_b128 v[162:165], v221 offset:1040
	v_add_f32_e32 v193, 0, v193
	s_waitcnt lgkmcnt(0)
	v_pk_fma_f32 v[182:183], v[182:183], v[146:147], v[162:163]
	v_pk_fma_f32 v[230:231], v[230:231], v[148:149], v[164:165]
	v_pk_mul_f32 v[182:183], v[182:183], s[52:53] op_sel_hi:[1,0]
	v_pk_mul_f32 v[230:231], v[230:231], s[52:53] op_sel_hi:[1,0]
	v_pk_fma_f32 v[134:135], s[12:13], v[134:135], v[182:183]
	v_pk_fma_f32 v[136:137], s[14:15], v[136:137], v[230:231]
	v_cvt_pk_f16_f32 v182, v134, v135
	v_add_f32_e32 v230, v134, v135
	v_mul_f32_e32 v135, v135, v135
	v_fmac_f32_e32 v135, v134, v134
	v_fmac_f32_e32 v135, v136, v136
	v_add_f32_e32 v230, v136, v230
	v_fmac_f32_e32 v135, v137, v137
	v_add_f32_e32 v230, v137, v230
	v_add_f32_e32 v225, v225, v135
	v_lshl_add_u64 v[134:135], s[76:77], 0, v[184:185]
	v_cvt_pk_f16_f32 v183, v136, v137
	v_add_f32_e32 v193, v193, v230
	v_lshl_add_u64 v[230:231], v[134:135], 0, v[190:191]
	s_waitcnt vmcnt(6)
	v_cvt_f32_f16_sdwa v137, v186 dst_sel:DWORD dst_unused:UNUSED_PAD src0_sel:WORD_1
	v_cvt_f32_f16_e32 v136, v186
	v_cvt_f32_f16_sdwa v135, v187 dst_sel:DWORD dst_unused:UNUSED_PAD src0_sel:WORD_1
	v_cvt_f32_f16_e32 v134, v187
	global_store_dwordx4 v[230:231], v[180:183], off
	v_sub_f32_e32 v136, v136, v192
	v_sub_f32_e32 v135, v135, v192
	v_sub_f32_e32 v134, v134, v192
	v_sub_f32_e32 v137, v137, v192
	v_pk_mul_f32 v[190:191], v[228:229], v[136:137] op_sel_hi:[0,1]
	v_pk_mul_f32 v[250:251], v[228:229], v[134:135] op_sel_hi:[0,1]
	ds_read_b128 v[180:183], v221 offset:512
	ds_read_b128 v[134:137], v221 offset:528
	ds_read_b128 v[184:187], v221 offset:1536
	s_waitcnt lgkmcnt(0)
	v_pk_fma_f32 v[190:191], v[190:191], v[180:181], v[184:185]
	s_nop 0
	v_pk_mul_f32 v[190:191], v[190:191], s[52:53] op_sel_hi:[1,0]
	v_pk_fma_f32 v[250:251], v[250:251], v[182:183], v[186:187]
	v_pk_fma_f32 v[126:127], s[12:13], v[126:127], v[190:191]
	v_pk_mul_f32 v[250:251], v[250:251], s[52:53] op_sel_hi:[1,0]
	v_cvt_pk_f16_f32 v190, v126, v127
	v_add_f32_e32 v249, v126, v127
	v_mul_f32_e32 v127, v127, v127
	v_pk_fma_f32 v[128:129], s[14:15], v[128:129], v[250:251]
	v_fmac_f32_e32 v127, v126, v126
	v_fmac_f32_e32 v127, v128, v128
	v_add_f32_e32 v249, v128, v249
	v_fmac_f32_e32 v127, v129, v129
	v_cvt_pk_f16_f32 v191, v128, v129
	v_add_f32_e32 v249, v129, v249
	v_add_f32_e32 v225, v225, v127
	v_cvt_f32_f16_sdwa v129, v188 dst_sel:DWORD dst_unused:UNUSED_PAD src0_sel:WORD_1
	v_cvt_f32_f16_e32 v128, v188
	v_cvt_f32_f16_sdwa v127, v189 dst_sel:DWORD dst_unused:UNUSED_PAD src0_sel:WORD_1
	v_cvt_f32_f16_e32 v126, v189
	v_sub_f32_e32 v129, v129, v192
	v_sub_f32_e32 v128, v128, v192
	v_sub_f32_e32 v127, v127, v192
	v_sub_f32_e32 v126, v126, v192
	v_add_f32_e32 v249, v193, v249
	v_pk_mul_f32 v[188:189], v[228:229], v[128:129] op_sel_hi:[0,1]
	v_pk_mul_f32 v[192:193], v[228:229], v[126:127] op_sel_hi:[0,1]
	ds_read_b128 v[126:129], v221 offset:1552
	s_waitcnt lgkmcnt(0)
	v_pk_fma_f32 v[188:189], v[188:189], v[134:135], v[126:127]
	v_pk_fma_f32 v[192:193], v[192:193], v[136:137], v[128:129]
	v_pk_mul_f32 v[188:189], v[188:189], s[52:53] op_sel_hi:[1,0]
	v_pk_mul_f32 v[192:193], v[192:193], s[52:53] op_sel_hi:[1,0]
	v_pk_fma_f32 v[122:123], s[12:13], v[122:123], v[188:189]
	v_pk_fma_f32 v[124:125], s[14:15], v[124:125], v[192:193]
	v_cvt_pk_f16_f32 v192, v122, v123
	v_add_f32_e32 v188, v122, v123
	v_mul_f32_e32 v123, v123, v123
	v_fmac_f32_e32 v123, v122, v122
	v_add_f32_e32 v188, v124, v188
	v_fmac_f32_e32 v123, v124, v124
	v_add_f32_e32 v188, v125, v188
	v_fmac_f32_e32 v123, v125, v125
	v_cvt_pk_f16_f32 v193, v124, v125
	v_add_f32_e32 v188, v249, v188
	v_add_f32_e32 v124, v225, v123
	v_mov_b32_e32 v122, v188
	v_mov_b32_e32 v125, v124
	global_store_dwordx4 v[230:231], v[190:193], off offset:256
	s_nop 1
	v_permlane16_swap_b32_e32 v122, v188
	v_permlane16_swap_b32_e32 v125, v124
	v_add_f32_e32 v122, v188, v122
	s_waitcnt lgkmcnt(0)
	v_add_f32_e32 v124, v124, v125
	v_mov_b32_e32 v123, v122
	v_mov_b32_e32 v125, v124
	s_nop 1
	v_permlane32_swap_b32_e32 v123, v122
	v_permlane32_swap_b32_e32 v125, v124
	s_and_saveexec_b64 s[30:31], s[6:7]
	s_cbranch_execz .LBB0_893
	v_lshlrev_b32_e32 v188, 1, v212
	v_ashrrev_i32_e32 v189, 31, v188
	v_lshl_add_u64 v[188:189], v[188:189], 2, s[16:17]
	s_waitcnt lgkmcnt(1)
	v_add_f32_e32 v122, v122, v123
	s_waitcnt lgkmcnt(0)
	v_add_f32_e32 v123, v124, v125
	global_atomic_add_f32 v[188:189], v122, off
	global_atomic_add_f32 v[188:189], v123, off offset:4
; #define LAS __attribute__((address_space(3)))
; DI unsigned pkh2(float a, float b) { typedef _Float16 h2 __attribute__((ext_vector_type(2))); h2 v; v[0] = (_Float16)a; v[1] = (_Float16)b; return __builtin_bit_cast(unsigned, v); }
;   DI void operator()(const f32x4 (&acc)[2][2][4][2], const pg8::Unit& u, int wr, int wc, int fr, int fq, LAS unsigned char* lds, int ui, int wid) const {
;     ...
;       for (int m = 0; m < 4; ++m) {
;         const int row = u.pm * 256 + ai * 128 + wr * 64 + m * 16 + fr; const float mu = rmu[ai * 4 + m], rstd = rrs[ai * 4 + m];
;         float rs = 0.f, rq = 0.f;
; #pragma unroll
;         for (int bj = 0; bj < 2; ++bj) {
;           u32x4 w;
; #pragma unroll
;           for (int n = 0; n < 2; ++n) {
;             f32x4 tp;
; #pragma unroll
;             for (int j = 0; j < 4; ++j) tp[j] = (float)tpv[m][bj][4 * n + j];
;             tp = (tp - mu) * rstd * (*(const LAS f32x4*)(gl + bj * 128 + 4 * n)) + *(const LAS f32x4*)(gl + 256 + bj * 128 + 4 * n);
;             const f32x4 tn = tp * ALPHA + acc[ai][bj][m][n] * scale;
;             w[2 * n] = pkh2(tn[0], tn[1]); w[2 * n + 1] = pkh2(tn[2], tn[3]);
;             rs += tn[0] + tn[1] + tn[2] + tn[3]; rq += tn[0] * tn[0] + tn[1] * tn[1] + tn[2] * tn[2] + tn[3] * tn[3];
;           }
;           *(u32x4*)(tb + (size_t)row * DM + col0 + bj * 128) = w;
;         }
;         rs += __shfl_xor(rs, 16); rs += __shfl_xor(rs, 32); rq += __shfl_xor(rq, 16); rq += __shfl_xor(rq, 32);
;         if (fq == 0) { atomicAdd(stats_new + 2 * row, rs); atomicAdd(stats_new + 2 * row + 1, rq); }
.LBB0_893:
	s_or_b64 exec, exec, s[30:31]
	s_waitcnt lgkmcnt(1)
	v_pk_mul_f32 v[122:123], v[170:171], s[44:45] op_sel_hi:[1,0]
	s_waitcnt lgkmcnt(0)
	s_waitcnt vmcnt(7)
	v_cvt_f32_f16_sdwa v125, v176 dst_sel:DWORD dst_unused:UNUSED_PAD src0_sel:WORD_1
	v_fma_f32 v123, -v122, v122, v123
	v_max_f32_e32 v123, 0, v123
	v_add_f32_e32 v123, 0x3727c5ac, v123
	v_mul_f32_e32 v124, 0x4b800000, v123
	v_cmp_gt_f32_e32 vcc, s36, v123
	v_cvt_f32_f16_sdwa v170, v177 dst_sel:DWORD dst_unused:UNUSED_PAD src0_sel:WORD_1
	v_cvt_f32_f16_e32 v176, v176
	v_cndmask_b32_e32 v123, v123, v124, vcc
	v_rsq_f32_e32 v123, v123
	v_sub_f32_e32 v171, v170, v122
	v_sub_f32_e32 v176, v176, v122
	v_mul_f32_e32 v124, 0x45800000, v123
	v_cndmask_b32_e32 v124, v123, v124, vcc
	v_cvt_f32_f16_e32 v123, v177
	v_sub_f32_e32 v177, v125, v122
	v_pk_mul_f32 v[176:177], v[124:125], v[176:177] op_sel_hi:[0,1]
	v_pk_fma_f32 v[176:177], v[150:151], v[176:177], v[154:155]
	v_sub_f32_e32 v170, v123, v122
	v_pk_mul_f32 v[170:171], v[124:125], v[170:171] op_sel_hi:[0,1]
	v_pk_fma_f32 v[170:171], v[152:153], v[170:171], v[156:157]
	v_pk_mul_f32 v[176:177], v[176:177], s[52:53] op_sel_hi:[1,0]
	v_pk_mul_f32 v[170:171], v[170:171], s[52:53] op_sel_hi:[1,0]
	s_nop 0
	v_pk_fma_f32 v[120:121], s[14:15], v[120:121], v[170:171]
	v_pk_fma_f32 v[170:171], s[12:13], v[118:119], v[176:177]
	v_cvt_f32_f16_e32 v177, v178
	v_mul_f32_e32 v125, v171, v171
	v_cvt_pk_f16_f32 v118, v170, v171
	v_add_f32_e32 v123, v170, v171
	v_fmac_f32_e32 v125, v170, v170
	v_cvt_f32_f16_sdwa v170, v178 dst_sel:DWORD dst_unused:UNUSED_PAD src0_sel:WORD_1
	v_cvt_pk_f16_f32 v119, v120, v121
	v_add_f32_e32 v123, v120, v123
	v_fmac_f32_e32 v125, v120, v120
	v_cvt_f32_f16_sdwa v120, v179 dst_sel:DWORD dst_unused:UNUSED_PAD src0_sel:WORD_1
	v_cvt_f32_f16_e32 v176, v179
	v_fmac_f32_e32 v125, v121, v121
	v_sub_f32_e32 v171, v170, v122
	v_sub_f32_e32 v170, v177, v122
	v_add_f32_e32 v123, v121, v123
	v_sub_f32_e32 v121, v120, v122
	v_sub_f32_e32 v120, v176, v122
	v_pk_mul_f32 v[170:171], v[124:125], v[170:171] op_sel_hi:[0,1]
	v_pk_mul_f32 v[120:121], v[124:125], v[120:121] op_sel_hi:[0,1]
	v_pk_fma_f32 v[170:171], v[170:171], v[146:147], v[162:163]
	v_pk_fma_f32 v[120:121], v[120:121], v[148:149], v[164:165]
	v_pk_mul_f32 v[170:171], v[170:171], s[52:53] op_sel_hi:[1,0]
	v_pk_mul_f32 v[120:121], v[120:121], s[52:53] op_sel_hi:[1,0]
	v_pk_fma_f32 v[114:115], s[12:13], v[114:115], v[170:171]
	v_pk_fma_f32 v[116:117], s[14:15], v[116:117], v[120:121]
	v_add_f32_e32 v170, v114, v115
	v_add_f32_e32 v170, v116, v170
	v_add_f32_e32 v123, 0, v123
	v_cvt_pk_f16_f32 v120, v114, v115
	v_add_f32_e32 v170, v117, v170
	v_mul_f32_e32 v115, v115, v115
	v_add_f32_e32 v123, v170, v123
	v_fmac_f32_e32 v115, v114, v114
	s_waitcnt vmcnt(6)
	v_cvt_f32_f16_sdwa v170, v172 dst_sel:DWORD dst_unused:UNUSED_PAD src0_sel:WORD_1
	v_cvt_f32_f16_e32 v172, v172
	v_cvt_pk_f16_f32 v121, v116, v117
	v_fmac_f32_e32 v115, v116, v116
	v_cvt_f32_f16_sdwa v116, v173 dst_sel:DWORD dst_unused:UNUSED_PAD src0_sel:WORD_1
	v_cvt_f32_f16_e32 v173, v173
	v_fmac_f32_e32 v115, v117, v117
	v_add_f32_e32 v125, v125, v115
	v_sub_f32_e32 v171, v170, v122
	v_sub_f32_e32 v170, v172, v122
	v_sub_f32_e32 v117, v116, v122
	v_sub_f32_e32 v116, v173, v122
	v_pk_mul_f32 v[170:171], v[124:125], v[170:171] op_sel_hi:[0,1]
	v_pk_mul_f32 v[116:117], v[124:125], v[116:117] op_sel_hi:[0,1]
	v_pk_fma_f32 v[170:171], v[170:171], v[180:181], v[184:185]
	v_pk_fma_f32 v[116:117], v[116:117], v[182:183], v[186:187]
	v_pk_mul_f32 v[170:171], v[170:171], s[52:53] op_sel_hi:[1,0]
	v_pk_mul_f32 v[116:117], v[116:117], s[52:53] op_sel_hi:[1,0]
	v_pk_fma_f32 v[110:111], s[12:13], v[110:111], v[170:171]
	v_pk_fma_f32 v[112:113], s[14:15], v[112:113], v[116:117]
	v_add_f32_e32 v116, v110, v111
	v_add_f32_e32 v116, v112, v116
	v_add_f32_e32 v116, v113, v116
	v_add_f32_e32 v170, v123, v116
	v_mul_f32_e32 v116, v111, v111
	v_fmac_f32_e32 v116, v110, v110
	v_fmac_f32_e32 v116, v112, v112
	v_fmac_f32_e32 v116, v113, v113
	v_add_f32_e32 v125, v125, v116
	v_cvt_f32_f16_sdwa v116, v175 dst_sel:DWORD dst_unused:UNUSED_PAD src0_sel:WORD_1
	v_cvt_f32_f16_sdwa v123, v174 dst_sel:DWORD dst_unused:UNUSED_PAD src0_sel:WORD_1
	v_cvt_f32_f16_e32 v171, v175
	v_cvt_f32_f16_e32 v172, v174
	v_sub_f32_e32 v117, v116, v122
	v_sub_f32_e32 v123, v123, v122
	v_sub_f32_e32 v116, v171, v122
	v_sub_f32_e32 v122, v172, v122
	v_pk_mul_f32 v[122:123], v[124:125], v[122:123] op_sel_hi:[0,1]
	v_pk_fma_f32 v[122:123], v[122:123], v[134:135], v[126:127]
	v_pk_mul_f32 v[116:117], v[124:125], v[116:117] op_sel_hi:[0,1]
	v_pk_mul_f32 v[122:123], v[122:123], s[52:53] op_sel_hi:[1,0]
	v_pk_fma_f32 v[116:117], v[116:117], v[136:137], v[128:129]
	v_pk_fma_f32 v[122:123], s[12:13], v[106:107], v[122:123]
	v_pk_mul_f32 v[116:117], v[116:117], s[52:53] op_sel_hi:[1,0]
	v_mul_f32_e32 v107, v123, v123
	v_pk_fma_f32 v[116:117], s[14:15], v[108:109], v[116:117]
	v_add_f32_e32 v106, v122, v123
	v_fmac_f32_e32 v107, v122, v122
	v_add_f32_e32 v106, v116, v106
	v_fmac_f32_e32 v107, v116, v116
	v_add_f32_e32 v106, v117, v106
	v_fmac_f32_e32 v107, v117, v117
	v_add_f32_e32 v106, v170, v106
	v_add_f32_e32 v109, v125, v107
	v_mov_b32_e32 v108, v106
	v_mov_b32_e32 v124, v109
	v_lshl_add_u64 v[114:115], s[76:77], 0, v[226:227]
	v_lshl_add_u64 v[114:115], v[210:211], 1, v[114:115]
	v_cvt_pk_f16_f32 v110, v110, v111
	s_nop 1
	v_permlane16_swap_b32_e32 v108, v106
	v_permlane16_swap_b32_e32 v124, v109
	v_add_f32_e32 v106, v106, v108
	s_waitcnt lgkmcnt(0)
	v_add_f32_e32 v108, v109, v124
	v_mov_b32_e32 v107, v106
	v_mov_b32_e32 v109, v108
	s_nop 1
	v_permlane32_swap_b32_e32 v107, v106
	v_permlane32_swap_b32_e32 v109, v108
	v_cvt_pk_f16_f32 v111, v112, v113
	v_cvt_pk_f16_f32 v112, v122, v123
	v_cvt_pk_f16_f32 v113, v116, v117
	global_store_dwordx4 v[114:115], v[118:121], off
	global_store_dwordx4 v[114:115], v[110:113], off offset:256
	s_and_saveexec_b64 s[30:31], s[6:7]
	s_cbranch_execz .LBB0_895
	v_lshlrev_b32_e32 v110, 1, v224
	v_ashrrev_i32_e32 v111, 31, v110
	v_lshl_add_u64 v[110:111], v[110:111], 2, s[16:17]
	s_waitcnt lgkmcnt(1)
	v_add_f32_e32 v106, v106, v107
	s_waitcnt lgkmcnt(0)
	v_add_f32_e32 v107, v108, v109
	global_atomic_add_f32 v[110:111], v106, off
	global_atomic_add_f32 v[110:111], v107, off offset:4
; #define LAS __attribute__((address_space(3)))
; DI unsigned pkh2(float a, float b) { typedef _Float16 h2 __attribute__((ext_vector_type(2))); h2 v; v[0] = (_Float16)a; v[1] = (_Float16)b; return __builtin_bit_cast(unsigned, v); }
;   DI void operator()(const f32x4 (&acc)[2][2][4][2], const pg8::Unit& u, int wr, int wc, int fr, int fq, LAS unsigned char* lds, int ui, int wid) const {
;     ...
;       for (int m = 0; m < 4; ++m) {
;         const int row = u.pm * 256 + ai * 128 + wr * 64 + m * 16 + fr; const float mu = rmu[ai * 4 + m], rstd = rrs[ai * 4 + m];
;         float rs = 0.f, rq = 0.f;
; #pragma unroll
;         for (int bj = 0; bj < 2; ++bj) {
;           u32x4 w;
; #pragma unroll
;           for (int n = 0; n < 2; ++n) {
;             f32x4 tp;
; #pragma unroll
;             for (int j = 0; j < 4; ++j) tp[j] = (float)tpv[m][bj][4 * n + j];
;             tp = (tp - mu) * rstd * (*(const LAS f32x4*)(gl + bj * 128 + 4 * n)) + *(const LAS f32x4*)(gl + 256 + bj * 128 + 4 * n);
;             const f32x4 tn = tp * ALPHA + acc[ai][bj][m][n] * scale;
;             w[2 * n] = pkh2(tn[0], tn[1]); w[2 * n + 1] = pkh2(tn[2], tn[3]);
;             rs += tn[0] + tn[1] + tn[2] + tn[3]; rq += tn[0] * tn[0] + tn[1] * tn[1] + tn[2] * tn[2] + tn[3] * tn[3];
;           }
;           *(u32x4*)(tb + (size_t)row * DM + col0 + bj * 128) = w;
;         }
;         rs += __shfl_xor(rs, 16); rs += __shfl_xor(rs, 32); rq += __shfl_xor(rq, 16); rq += __shfl_xor(rq, 32);
;         if (fq == 0) { atomicAdd(stats_new + 2 * row, rs); atomicAdd(stats_new + 2 * row + 1, rq); }
.LBB0_895:
	s_or_b64 exec, exec, s[30:31]
	s_waitcnt lgkmcnt(1)
	v_pk_mul_f32 v[106:107], v[130:131], s[44:45] op_sel_hi:[1,0]
	s_waitcnt lgkmcnt(0)
	s_waitcnt vmcnt(7)
	v_cvt_f32_f16_sdwa v109, v166 dst_sel:DWORD dst_unused:UNUSED_PAD src0_sel:WORD_1
	v_fma_f32 v107, -v106, v106, v107
	v_max_f32_e32 v107, 0, v107
	v_add_f32_e32 v107, 0x3727c5ac, v107
	v_mul_f32_e32 v108, 0x4b800000, v107
	v_cmp_gt_f32_e32 vcc, s36, v107
	v_cvt_f32_f16_sdwa v110, v167 dst_sel:DWORD dst_unused:UNUSED_PAD src0_sel:WORD_1
	v_cvt_f32_f16_e32 v112, v166
	v_cndmask_b32_e32 v107, v107, v108, vcc
	v_rsq_f32_e32 v107, v107
	v_sub_f32_e32 v111, v110, v106
	v_sub_f32_e32 v113, v109, v106
	v_sub_f32_e32 v112, v112, v106
	v_mul_f32_e32 v108, 0x45800000, v107
	v_cndmask_b32_e32 v108, v107, v108, vcc
	v_cvt_f32_f16_e32 v107, v167
	v_pk_mul_f32 v[112:113], v[108:109], v[112:113] op_sel_hi:[0,1]
	v_pk_fma_f32 v[112:113], v[150:151], v[112:113], v[154:155]
	v_sub_f32_e32 v110, v107, v106
	v_pk_mul_f32 v[110:111], v[108:109], v[110:111] op_sel_hi:[0,1]
	v_pk_fma_f32 v[110:111], v[152:153], v[110:111], v[156:157]
	v_pk_mul_f32 v[112:113], v[112:113], s[52:53] op_sel_hi:[1,0]
	v_pk_mul_f32 v[110:111], v[110:111], s[52:53] op_sel_hi:[1,0]
	s_nop 0
	v_pk_fma_f32 v[104:105], s[14:15], v[104:105], v[110:111]
	v_pk_fma_f32 v[110:111], s[12:13], v[102:103], v[112:113]
	v_cvt_f32_f16_e32 v113, v168
	v_mul_f32_e32 v109, v111, v111
	v_cvt_pk_f16_f32 v102, v110, v111
	v_add_f32_e32 v107, v110, v111
	v_fmac_f32_e32 v109, v110, v110
	v_cvt_f32_f16_sdwa v110, v168 dst_sel:DWORD dst_unused:UNUSED_PAD src0_sel:WORD_1
	v_cvt_pk_f16_f32 v103, v104, v105
	v_add_f32_e32 v107, v104, v107
	v_fmac_f32_e32 v109, v104, v104
	v_cvt_f32_f16_sdwa v104, v169 dst_sel:DWORD dst_unused:UNUSED_PAD src0_sel:WORD_1
	v_cvt_f32_f16_e32 v112, v169
	v_fmac_f32_e32 v109, v105, v105
	v_sub_f32_e32 v111, v110, v106
	v_sub_f32_e32 v110, v113, v106
	v_add_f32_e32 v107, v105, v107
	v_sub_f32_e32 v105, v104, v106
	v_sub_f32_e32 v104, v112, v106
	v_pk_mul_f32 v[110:111], v[108:109], v[110:111] op_sel_hi:[0,1]
	v_pk_mul_f32 v[104:105], v[108:109], v[104:105] op_sel_hi:[0,1]
	v_pk_fma_f32 v[110:111], v[146:147], v[110:111], v[162:163]
	v_pk_fma_f32 v[104:105], v[148:149], v[104:105], v[164:165]
	v_pk_mul_f32 v[110:111], v[110:111], s[52:53] op_sel_hi:[1,0]
	v_pk_mul_f32 v[104:105], v[104:105], s[52:53] op_sel_hi:[1,0]
	v_pk_fma_f32 v[98:99], s[12:13], v[98:99], v[110:111]
	v_pk_fma_f32 v[100:101], s[14:15], v[100:101], v[104:105]
	v_add_f32_e32 v110, v98, v99
	v_add_f32_e32 v110, v100, v110
	v_add_f32_e32 v107, 0, v107
	v_cvt_pk_f16_f32 v104, v98, v99
	v_add_f32_e32 v110, v101, v110
	v_mul_f32_e32 v99, v99, v99
	v_add_f32_e32 v107, v110, v107
	v_fmac_f32_e32 v99, v98, v98
	s_waitcnt vmcnt(6)
	v_cvt_f32_f16_sdwa v110, v158 dst_sel:DWORD dst_unused:UNUSED_PAD src0_sel:WORD_1
	v_cvt_f32_f16_e32 v113, v158
	v_cvt_pk_f16_f32 v105, v100, v101
	v_fmac_f32_e32 v99, v100, v100
	v_cvt_f32_f16_sdwa v100, v159 dst_sel:DWORD dst_unused:UNUSED_PAD src0_sel:WORD_1
	v_cvt_f32_f16_e32 v112, v159
	v_fmac_f32_e32 v99, v101, v101
	v_add_f32_e32 v109, v109, v99
	v_sub_f32_e32 v111, v110, v106
	v_sub_f32_e32 v110, v113, v106
	v_sub_f32_e32 v101, v100, v106
	v_sub_f32_e32 v100, v112, v106
	v_pk_mul_f32 v[110:111], v[108:109], v[110:111] op_sel_hi:[0,1]
	v_pk_mul_f32 v[100:101], v[108:109], v[100:101] op_sel_hi:[0,1]
	v_pk_fma_f32 v[110:111], v[110:111], v[180:181], v[184:185]
	v_pk_fma_f32 v[100:101], v[100:101], v[182:183], v[186:187]
	v_pk_mul_f32 v[110:111], v[110:111], s[52:53] op_sel_hi:[1,0]
	v_pk_mul_f32 v[100:101], v[100:101], s[52:53] op_sel_hi:[1,0]
	v_pk_fma_f32 v[94:95], s[12:13], v[94:95], v[110:111]
	v_pk_fma_f32 v[96:97], s[14:15], v[96:97], v[100:101]
	v_add_f32_e32 v100, v94, v95
	v_add_f32_e32 v100, v96, v100
	v_add_f32_e32 v100, v97, v100
	v_add_f32_e32 v110, v100, v107
	v_mul_f32_e32 v100, v95, v95
	v_fmac_f32_e32 v100, v94, v94
	v_fmac_f32_e32 v100, v96, v96
	v_fmac_f32_e32 v100, v97, v97
	v_add_f32_e32 v109, v109, v100
	v_cvt_f32_f16_sdwa v100, v161 dst_sel:DWORD dst_unused:UNUSED_PAD src0_sel:WORD_1
	v_cvt_f32_f16_sdwa v107, v160 dst_sel:DWORD dst_unused:UNUSED_PAD src0_sel:WORD_1
	v_cvt_f32_f16_e32 v111, v161
	v_cvt_f32_f16_e32 v112, v160
	v_sub_f32_e32 v101, v100, v106
	v_sub_f32_e32 v107, v107, v106
	v_sub_f32_e32 v100, v111, v106
	v_sub_f32_e32 v106, v112, v106
	v_pk_mul_f32 v[106:107], v[108:109], v[106:107] op_sel_hi:[0,1]
	v_pk_fma_f32 v[106:107], v[106:107], v[134:135], v[126:127]
	v_pk_mul_f32 v[100:101], v[108:109], v[100:101] op_sel_hi:[0,1]
	v_pk_mul_f32 v[106:107], v[106:107], s[52:53] op_sel_hi:[1,0]
	v_pk_fma_f32 v[100:101], v[100:101], v[136:137], v[128:129]
	v_pk_fma_f32 v[106:107], s[12:13], v[90:91], v[106:107]
	v_pk_mul_f32 v[100:101], v[100:101], s[52:53] op_sel_hi:[1,0]
	v_mul_f32_e32 v91, v107, v107
	v_pk_fma_f32 v[100:101], s[14:15], v[92:93], v[100:101]
	v_add_f32_e32 v90, v106, v107
	v_fmac_f32_e32 v91, v106, v106
	v_add_f32_e32 v90, v100, v90
	v_fmac_f32_e32 v91, v100, v100
	v_add_f32_e32 v90, v101, v90
	v_fmac_f32_e32 v91, v101, v101
	v_add_f32_e32 v90, v110, v90
	v_add_f32_e32 v93, v109, v91
	v_mov_b32_e32 v92, v90
	v_mov_b32_e32 v108, v93
	v_lshl_add_u64 v[98:99], s[76:77], 0, v[222:223]
	v_lshl_add_u64 v[98:99], v[210:211], 1, v[98:99]
	v_cvt_pk_f16_f32 v94, v94, v95
	s_nop 1
	v_permlane16_swap_b32_e32 v92, v90
	v_permlane16_swap_b32_e32 v108, v93
	v_add_f32_e32 v90, v90, v92
	s_waitcnt lgkmcnt(0)
	v_add_f32_e32 v92, v93, v108
	v_mov_b32_e32 v91, v90
	v_mov_b32_e32 v93, v92
	s_nop 1
	v_permlane32_swap_b32_e32 v91, v90
	v_permlane32_swap_b32_e32 v93, v92
	v_cvt_pk_f16_f32 v95, v96, v97
	v_cvt_pk_f16_f32 v96, v106, v107
	v_cvt_pk_f16_f32 v97, v100, v101
	global_store_dwordx4 v[98:99], v[102:105], off
	global_store_dwordx4 v[98:99], v[94:97], off offset:256
	s_and_saveexec_b64 s[30:31], s[6:7]
	s_cbranch_execz .LBB0_897
	v_lshlrev_b32_e32 v94, 1, v220
	v_ashrrev_i32_e32 v95, 31, v94
	v_lshl_add_u64 v[94:95], v[94:95], 2, s[16:17]
	s_waitcnt lgkmcnt(1)
	v_add_f32_e32 v90, v90, v91
	s_waitcnt lgkmcnt(0)
	v_add_f32_e32 v91, v92, v93
	global_atomic_add_f32 v[94:95], v90, off
	global_atomic_add_f32 v[94:95], v91, off offset:4
; #define LAS __attribute__((address_space(3)))
; DI unsigned pkh2(float a, float b) { typedef _Float16 h2 __attribute__((ext_vector_type(2))); h2 v; v[0] = (_Float16)a; v[1] = (_Float16)b; return __builtin_bit_cast(unsigned, v); }
;   DI void operator()(const f32x4 (&acc)[2][2][4][2], const pg8::Unit& u, int wr, int wc, int fr, int fq, LAS unsigned char* lds, int ui, int wid) const {
;     ...
;       for (int m = 0; m < 4; ++m) {
;         const int row = u.pm * 256 + ai * 128 + wr * 64 + m * 16 + fr; const float mu = rmu[ai * 4 + m], rstd = rrs[ai * 4 + m];
;         float rs = 0.f, rq = 0.f;
; #pragma unroll
;         for (int bj = 0; bj < 2; ++bj) {
;           u32x4 w;
; #pragma unroll
;           for (int n = 0; n < 2; ++n) {
;             f32x4 tp;
; #pragma unroll
;             for (int j = 0; j < 4; ++j) tp[j] = (float)tpv[m][bj][4 * n + j];
;             tp = (tp - mu) * rstd * (*(const LAS f32x4*)(gl + bj * 128 + 4 * n)) + *(const LAS f32x4*)(gl + 256 + bj * 128 + 4 * n);
;             const f32x4 tn = tp * ALPHA + acc[ai][bj][m][n] * scale;
;             w[2 * n] = pkh2(tn[0], tn[1]); w[2 * n + 1] = pkh2(tn[2], tn[3]);
;             rs += tn[0] + tn[1] + tn[2] + tn[3]; rq += tn[0] * tn[0] + tn[1] * tn[1] + tn[2] * tn[2] + tn[3] * tn[3];
;           }
;           *(u32x4*)(tb + (size_t)row * DM + col0 + bj * 128) = w;
;         }
;         rs += __shfl_xor(rs, 16); rs += __shfl_xor(rs, 32); rq += __shfl_xor(rq, 16); rq += __shfl_xor(rq, 32);
;         if (fq == 0) { atomicAdd(stats_new + 2 * row, rs); atomicAdd(stats_new + 2 * row + 1, rq); }
.LBB0_897:
	s_or_b64 exec, exec, s[30:31]
	s_waitcnt lgkmcnt(1)
	v_pk_mul_f32 v[90:91], v[132:133], s[44:45] op_sel_hi:[1,0]
	s_waitcnt lgkmcnt(0)
	s_waitcnt vmcnt(7)
	v_cvt_f32_f16_sdwa v93, v142 dst_sel:DWORD dst_unused:UNUSED_PAD src0_sel:WORD_1
	v_fma_f32 v91, -v90, v90, v91
	v_max_f32_e32 v91, 0, v91
	v_add_f32_e32 v91, 0x3727c5ac, v91
	v_mul_f32_e32 v92, 0x4b800000, v91
	v_cmp_gt_f32_e32 vcc, s36, v91
	v_cvt_f32_f16_sdwa v94, v143 dst_sel:DWORD dst_unused:UNUSED_PAD src0_sel:WORD_1
	v_cvt_f32_f16_e32 v96, v142
	v_cndmask_b32_e32 v91, v91, v92, vcc
	v_rsq_f32_e32 v91, v91
	v_sub_f32_e32 v95, v94, v90
	v_sub_f32_e32 v97, v93, v90
	v_sub_f32_e32 v96, v96, v90
	v_mul_f32_e32 v92, 0x45800000, v91
	v_cndmask_b32_e32 v92, v91, v92, vcc
	v_cvt_f32_f16_e32 v91, v143
	v_pk_mul_f32 v[96:97], v[92:93], v[96:97] op_sel_hi:[0,1]
	v_pk_fma_f32 v[96:97], v[150:151], v[96:97], v[154:155]
	v_sub_f32_e32 v94, v91, v90
	v_pk_mul_f32 v[94:95], v[92:93], v[94:95] op_sel_hi:[0,1]
	v_pk_fma_f32 v[94:95], v[152:153], v[94:95], v[156:157]
	v_pk_mul_f32 v[96:97], v[96:97], s[52:53] op_sel_hi:[1,0]
	v_pk_mul_f32 v[94:95], v[94:95], s[52:53] op_sel_hi:[1,0]
	s_nop 0
	v_pk_fma_f32 v[88:89], s[14:15], v[88:89], v[94:95]
	v_pk_fma_f32 v[94:95], s[12:13], v[86:87], v[96:97]
	v_cvt_f32_f16_e32 v97, v144
	v_mul_f32_e32 v93, v95, v95
	v_cvt_pk_f16_f32 v86, v94, v95
	v_add_f32_e32 v91, v94, v95
	v_fmac_f32_e32 v93, v94, v94
	v_cvt_f32_f16_sdwa v94, v144 dst_sel:DWORD dst_unused:UNUSED_PAD src0_sel:WORD_1
	v_cvt_pk_f16_f32 v87, v88, v89
	v_add_f32_e32 v91, v88, v91
	v_fmac_f32_e32 v93, v88, v88
	v_cvt_f32_f16_sdwa v88, v145 dst_sel:DWORD dst_unused:UNUSED_PAD src0_sel:WORD_1
	v_cvt_f32_f16_e32 v96, v145
	v_fmac_f32_e32 v93, v89, v89
	v_sub_f32_e32 v95, v94, v90
	v_sub_f32_e32 v94, v97, v90
	v_add_f32_e32 v91, v89, v91
	v_sub_f32_e32 v89, v88, v90
	v_sub_f32_e32 v88, v96, v90
	v_pk_mul_f32 v[94:95], v[92:93], v[94:95] op_sel_hi:[0,1]
	v_pk_mul_f32 v[88:89], v[92:93], v[88:89] op_sel_hi:[0,1]
	v_pk_fma_f32 v[94:95], v[146:147], v[94:95], v[162:163]
	v_pk_fma_f32 v[88:89], v[148:149], v[88:89], v[164:165]
	v_pk_mul_f32 v[94:95], v[94:95], s[52:53] op_sel_hi:[1,0]
	v_pk_mul_f32 v[88:89], v[88:89], s[52:53] op_sel_hi:[1,0]
	v_pk_fma_f32 v[82:83], s[12:13], v[82:83], v[94:95]
	v_pk_fma_f32 v[84:85], s[14:15], v[84:85], v[88:89]
	v_add_f32_e32 v94, v82, v83
	v_add_f32_e32 v94, v84, v94
	v_add_f32_e32 v91, 0, v91
	v_cvt_pk_f16_f32 v88, v82, v83
	v_add_f32_e32 v94, v85, v94
	v_mul_f32_e32 v83, v83, v83
	v_add_f32_e32 v91, v94, v91
	v_fmac_f32_e32 v83, v82, v82
	s_waitcnt vmcnt(6)
	v_cvt_f32_f16_sdwa v94, v138 dst_sel:DWORD dst_unused:UNUSED_PAD src0_sel:WORD_1
	v_cvt_f32_f16_e32 v97, v138
	v_cvt_pk_f16_f32 v89, v84, v85
	v_fmac_f32_e32 v83, v84, v84
	v_cvt_f32_f16_sdwa v84, v139 dst_sel:DWORD dst_unused:UNUSED_PAD src0_sel:WORD_1
	v_cvt_f32_f16_e32 v96, v139
	v_fmac_f32_e32 v83, v85, v85
	v_add_f32_e32 v93, v93, v83
	v_sub_f32_e32 v95, v94, v90
	v_sub_f32_e32 v94, v97, v90
	v_sub_f32_e32 v85, v84, v90
	v_sub_f32_e32 v84, v96, v90
	v_pk_mul_f32 v[94:95], v[92:93], v[94:95] op_sel_hi:[0,1]
	v_pk_mul_f32 v[84:85], v[92:93], v[84:85] op_sel_hi:[0,1]
	v_pk_fma_f32 v[94:95], v[180:181], v[94:95], v[184:185]
	v_pk_fma_f32 v[84:85], v[182:183], v[84:85], v[186:187]
	v_pk_mul_f32 v[94:95], v[94:95], s[52:53] op_sel_hi:[1,0]
	v_pk_mul_f32 v[84:85], v[84:85], s[52:53] op_sel_hi:[1,0]
	v_pk_fma_f32 v[78:79], s[12:13], v[78:79], v[94:95]
	v_pk_fma_f32 v[80:81], s[14:15], v[80:81], v[84:85]
	v_add_f32_e32 v84, v78, v79
	v_add_f32_e32 v84, v80, v84
	v_add_f32_e32 v84, v81, v84
	v_add_f32_e32 v94, v84, v91
	v_mul_f32_e32 v84, v79, v79
	v_fmac_f32_e32 v84, v78, v78
	v_fmac_f32_e32 v84, v80, v80
	v_fmac_f32_e32 v84, v81, v81
	v_add_f32_e32 v93, v93, v84
	v_cvt_f32_f16_sdwa v84, v141 dst_sel:DWORD dst_unused:UNUSED_PAD src0_sel:WORD_1
	v_cvt_f32_f16_sdwa v91, v140 dst_sel:DWORD dst_unused:UNUSED_PAD src0_sel:WORD_1
	v_cvt_f32_f16_e32 v95, v141
	v_cvt_f32_f16_e32 v96, v140
	v_sub_f32_e32 v85, v84, v90
	v_sub_f32_e32 v91, v91, v90
	v_sub_f32_e32 v84, v95, v90
	v_sub_f32_e32 v90, v96, v90
	v_pk_mul_f32 v[90:91], v[92:93], v[90:91] op_sel_hi:[0,1]
	v_pk_fma_f32 v[90:91], v[90:91], v[134:135], v[126:127]
	v_pk_mul_f32 v[84:85], v[92:93], v[84:85] op_sel_hi:[0,1]
	v_pk_mul_f32 v[90:91], v[90:91], s[52:53] op_sel_hi:[1,0]
	v_pk_fma_f32 v[84:85], v[84:85], v[136:137], v[128:129]
	v_pk_fma_f32 v[90:91], s[12:13], v[74:75], v[90:91]
	v_pk_mul_f32 v[84:85], v[84:85], s[52:53] op_sel_hi:[1,0]
	v_mul_f32_e32 v75, v91, v91
	v_pk_fma_f32 v[84:85], s[14:15], v[76:77], v[84:85]
	v_add_f32_e32 v74, v90, v91
	v_fmac_f32_e32 v75, v90, v90
	v_add_f32_e32 v74, v84, v74
	v_fmac_f32_e32 v75, v84, v84
	v_add_f32_e32 v74, v85, v74
	v_fmac_f32_e32 v75, v85, v85
	v_add_f32_e32 v74, v74, v94
	v_add_f32_e32 v77, v75, v93
	v_mov_b32_e32 v76, v74
	v_mov_b32_e32 v92, v77
	v_lshl_add_u64 v[82:83], s[76:77], 0, v[218:219]
	v_lshl_add_u64 v[82:83], v[210:211], 1, v[82:83]
	v_cvt_pk_f16_f32 v78, v78, v79
	s_nop 1
	v_permlane16_swap_b32_e32 v76, v74
	v_permlane16_swap_b32_e32 v92, v77
	v_add_f32_e32 v74, v74, v76
	s_waitcnt lgkmcnt(0)
	v_add_f32_e32 v76, v77, v92
	v_mov_b32_e32 v75, v74
	v_mov_b32_e32 v77, v76
	s_nop 1
	v_permlane32_swap_b32_e32 v75, v74
	v_permlane32_swap_b32_e32 v77, v76
	v_cvt_pk_f16_f32 v79, v80, v81
	v_cvt_pk_f16_f32 v80, v90, v91
	v_cvt_pk_f16_f32 v81, v84, v85
	global_store_dwordx4 v[82:83], v[86:89], off
	global_store_dwordx4 v[82:83], v[78:81], off offset:256
	s_and_saveexec_b64 s[30:31], s[6:7]
	s_cbranch_execz .LBB0_899
	v_lshlrev_b32_e32 v78, 1, v214
	v_ashrrev_i32_e32 v79, 31, v78
	v_lshl_add_u64 v[78:79], v[78:79], 2, s[16:17]
	s_waitcnt lgkmcnt(1)
	v_add_f32_e32 v74, v74, v75
	s_waitcnt lgkmcnt(0)
	v_add_f32_e32 v75, v76, v77
	global_atomic_add_f32 v[78:79], v74, off
	global_atomic_add_f32 v[78:79], v75, off offset:4
; #define LAS __attribute__((address_space(3)))
; DI unsigned pkh2(float a, float b) { typedef _Float16 h2 __attribute__((ext_vector_type(2))); h2 v; v[0] = (_Float16)a; v[1] = (_Float16)b; return __builtin_bit_cast(unsigned, v); }
;   DI void operator()(const f32x4 (&acc)[2][2][4][2], const pg8::Unit& u, int wr, int wc, int fr, int fq, LAS unsigned char* lds, int ui, int wid) const {
;     ...
;     for (int ai = 0; ai < 2; ++ai) {
;       half8 tpv[4][2];
; #pragma unroll
;       for (int m = 0; m < 4; ++m)
; #pragma unroll
;         for (int bj = 0; bj < 2; ++bj) tpv[m][bj] = *(const half8*)(tb + (size_t)(u.pm * 256 + ai * 128 + wr * 64 + m * 16 + fr) * DM + col0 + bj * 128);
; #pragma unroll
;       for (int m = 0; m < 4; ++m) {
;         const int row = u.pm * 256 + ai * 128 + wr * 64 + m * 16 + fr; const float mu = rmu[ai * 4 + m], rstd = rrs[ai * 4 + m];
;         float rs = 0.f, rq = 0.f;
; #pragma unroll
;         for (int bj = 0; bj < 2; ++bj) {
;           u32x4 w;
; #pragma unroll
;           for (int n = 0; n < 2; ++n) {
;             f32x4 tp;
; #pragma unroll
;             for (int j = 0; j < 4; ++j) tp[j] = (float)tpv[m][bj][4 * n + j];
;             tp = (tp - mu) * rstd * (*(const LAS f32x4*)(gl + bj * 128 + 4 * n)) + *(const LAS f32x4*)(gl + 256 + bj * 128 + 4 * n);
;             const f32x4 tn = tp * ALPHA + acc[ai][bj][m][n] * scale;
;             w[2 * n] = pkh2(tn[0], tn[1]); w[2 * n + 1] = pkh2(tn[2], tn[3]);
;             rs += tn[0] + tn[1] + tn[2] + tn[3]; rq += tn[0] * tn[0] + tn[1] * tn[1] + tn[2] * tn[2] + tn[3] * tn[3];
;           }
;           *(u32x4*)(tb + (size_t)row * DM + col0 + bj * 128) = w;
.LBB0_899:
	s_or_b64 exec, exec, s[30:31]
	v_pk_mul_f32 v[66:67], v[66:67], s[44:45] op_sel_hi:[1,0]
	v_add_u32_e32 v134, 0x80, v212
	v_fma_f32 v67, -v66, v66, v67
	v_max_f32_e32 v67, 0, v67
	v_add_f32_e32 v67, 0x3727c5ac, v67
	v_cmp_gt_f32_e32 vcc, s36, v67
	v_mul_f32_e32 v74, 0x4b800000, v67
	v_ashrrev_i32_e32 v135, 31, v134
	v_cndmask_b32_e32 v67, v67, v74, vcc
	v_rsq_f32_e32 v67, v67
	v_lshlrev_b64 v[110:111], 11, v[134:135]
	v_add_u32_e32 v130, 0x90, v212
	v_mul_f32_e32 v74, 0x45800000, v67
	v_cndmask_b32_e32 v120, v67, v74, vcc
	s_waitcnt lgkmcnt(1)
	v_lshl_add_u64 v[74:75], v[216:217], 0, v[110:111]
	global_load_dwordx4 v[116:119], v[74:75], off
	global_load_dwordx4 v[112:115], v[74:75], off offset:256
	v_ashrrev_i32_e32 v131, 31, v130
	v_add_u32_e32 v126, 0xa0, v212
	v_lshlrev_b64 v[132:133], 11, v[130:131]
	v_ashrrev_i32_e32 v127, 31, v126
	v_add_u32_e32 v122, 0xb0, v212
	v_lshlrev_b64 v[128:129], 11, v[126:127]
	v_ashrrev_i32_e32 v123, 31, v122
	v_lshl_add_u64 v[74:75], v[216:217], 0, v[132:133]
	v_lshlrev_b64 v[124:125], 11, v[122:123]
	global_load_dwordx4 v[106:109], v[74:75], off
	global_load_dwordx4 v[102:105], v[74:75], off offset:256
	v_lshl_add_u64 v[74:75], v[216:217], 0, v[128:129]
	global_load_dwordx4 v[98:101], v[74:75], off
	global_load_dwordx4 v[86:89], v[74:75], off offset:256
	v_lshl_add_u64 v[74:75], v[216:217], 0, v[124:125]
	global_load_dwordx4 v[78:81], v[74:75], off
	s_waitcnt lgkmcnt(0)
	global_load_dwordx4 v[74:77], v[74:75], off offset:256
	s_waitcnt vmcnt(7)
	v_cvt_f32_f16_sdwa v67, v116 dst_sel:DWORD dst_unused:UNUSED_PAD src0_sel:WORD_1
	v_cvt_f32_f16_e32 v84, v116
	v_cvt_f32_f16_sdwa v83, v117 dst_sel:DWORD dst_unused:UNUSED_PAD src0_sel:WORD_1
	v_cvt_f32_f16_e32 v82, v117
	v_sub_f32_e32 v85, v67, v66
	v_sub_f32_e32 v84, v84, v66
	v_sub_f32_e32 v83, v83, v66
	v_sub_f32_e32 v82, v82, v66
	v_pk_mul_f32 v[116:117], v[120:121], v[84:85] op_sel_hi:[0,1]
	v_pk_mul_f32 v[136:137], v[120:121], v[82:83] op_sel_hi:[0,1]
	ds_read_b128 v[90:93], v221
	ds_read_b128 v[82:85], v221 offset:16
	ds_read_b128 v[94:97], v221 offset:1024
	s_waitcnt lgkmcnt(0)
	v_pk_fma_f32 v[116:117], v[116:117], v[90:91], v[94:95]
	s_nop 0
	v_pk_mul_f32 v[116:117], v[116:117], s[52:53] op_sel_hi:[1,0]
	v_pk_fma_f32 v[136:137], v[136:137], v[92:93], v[96:97]
	v_pk_fma_f32 v[70:71], s[12:13], v[70:71], v[116:117]
	v_pk_mul_f32 v[136:137], v[136:137], s[52:53] op_sel_hi:[1,0]
	v_mul_f32_e32 v121, v71, v71
	v_pk_fma_f32 v[72:73], s[14:15], v[72:73], v[136:137]
	v_add_f32_e32 v67, v70, v71
	v_fmac_f32_e32 v121, v70, v70
	v_add_f32_e32 v67, v72, v67
	v_fmac_f32_e32 v121, v72, v72
	v_cvt_pk_f16_f32 v116, v70, v71
	v_cvt_pk_f16_f32 v117, v72, v73
	v_add_f32_e32 v67, v73, v67
	v_fmac_f32_e32 v121, v73, v73
	v_cvt_f32_f16_sdwa v73, v118 dst_sel:DWORD dst_unused:UNUSED_PAD src0_sel:WORD_1
	v_cvt_f32_f16_e32 v72, v118
	v_cvt_f32_f16_sdwa v71, v119 dst_sel:DWORD dst_unused:UNUSED_PAD src0_sel:WORD_1
	v_cvt_f32_f16_e32 v70, v119
	v_sub_f32_e32 v73, v73, v66
	v_sub_f32_e32 v72, v72, v66
	v_sub_f32_e32 v71, v71, v66
	v_sub_f32_e32 v70, v70, v66
	v_pk_mul_f32 v[118:119], v[120:121], v[72:73] op_sel_hi:[0,1]
	v_pk_mul_f32 v[136:137], v[120:121], v[70:71] op_sel_hi:[0,1]
	ds_read_b128 v[70:73], v221 offset:1040
	v_add_f32_e32 v67, 0, v67
	s_waitcnt lgkmcnt(0)
	v_pk_fma_f32 v[118:119], v[118:119], v[82:83], v[70:71]
	s_nop 0
	v_pk_mul_f32 v[118:119], v[118:119], s[52:53] op_sel_hi:[1,0]
	v_pk_fma_f32 v[136:137], v[136:137], v[84:85], v[72:73]
	v_pk_fma_f32 v[62:63], s[12:13], v[62:63], v[118:119]
	v_pk_mul_f32 v[136:137], v[136:137], s[52:53] op_sel_hi:[1,0]
	v_cvt_pk_f16_f32 v118, v62, v63
	v_add_f32_e32 v123, v62, v63
	v_mul_f32_e32 v63, v63, v63
	v_pk_fma_f32 v[64:65], s[14:15], v[64:65], v[136:137]
	v_fmac_f32_e32 v63, v62, v62
	v_fmac_f32_e32 v63, v64, v64
	v_fmac_f32_e32 v63, v65, v65
	v_add_f32_e32 v123, v64, v123
	v_add_f32_e32 v121, v121, v63
	v_lshl_add_u64 v[62:63], s[76:77], 0, v[110:111]
	v_cvt_pk_f16_f32 v119, v64, v65
	v_add_f32_e32 v123, v65, v123
	v_lshl_add_u64 v[136:137], v[210:211], 1, v[62:63]
	s_waitcnt vmcnt(6)
	v_cvt_f32_f16_sdwa v65, v112 dst_sel:DWORD dst_unused:UNUSED_PAD src0_sel:WORD_1
	v_cvt_f32_f16_e32 v64, v112
	v_cvt_f32_f16_sdwa v63, v113 dst_sel:DWORD dst_unused:UNUSED_PAD src0_sel:WORD_1
	v_cvt_f32_f16_e32 v62, v113
	global_store_dwordx4 v[136:137], v[116:119], off
	v_sub_f32_e32 v64, v64, v66
	v_sub_f32_e32 v63, v63, v66
	v_sub_f32_e32 v62, v62, v66
	v_sub_f32_e32 v65, v65, v66
	v_pk_mul_f32 v[116:117], v[120:121], v[64:65] op_sel_hi:[0,1]
	v_pk_mul_f32 v[118:119], v[120:121], v[62:63] op_sel_hi:[0,1]
	ds_read_b128 v[62:65], v221 offset:512
	ds_read_b128 v[110:113], v221 offset:1536
	v_add_f32_e32 v67, v67, v123
	s_waitcnt lgkmcnt(0)
	v_pk_fma_f32 v[116:117], v[116:117], v[62:63], v[110:111]
	v_pk_fma_f32 v[118:119], v[118:119], v[64:65], v[112:113]
	v_pk_mul_f32 v[116:117], v[116:117], s[52:53] op_sel_hi:[1,0]
	v_pk_mul_f32 v[118:119], v[118:119], s[52:53] op_sel_hi:[1,0]
	v_pk_fma_f32 v[54:55], s[12:13], v[54:55], v[116:117]
	v_pk_fma_f32 v[56:57], s[14:15], v[56:57], v[118:119]
	v_cvt_pk_f16_f32 v118, v54, v55
	v_add_f32_e32 v116, v54, v55
	v_mul_f32_e32 v55, v55, v55
	v_fmac_f32_e32 v55, v54, v54
	v_fmac_f32_e32 v55, v56, v56
	v_add_f32_e32 v116, v56, v116
	v_fmac_f32_e32 v55, v57, v57
	v_cvt_pk_f16_f32 v119, v56, v57
	v_add_f32_e32 v116, v57, v116
	v_add_f32_e32 v127, v121, v55
	v_cvt_f32_f16_sdwa v57, v114 dst_sel:DWORD dst_unused:UNUSED_PAD src0_sel:WORD_1
	v_cvt_f32_f16_e32 v56, v114
	v_cvt_f32_f16_sdwa v55, v115 dst_sel:DWORD dst_unused:UNUSED_PAD src0_sel:WORD_1
	v_cvt_f32_f16_e32 v54, v115
	v_sub_f32_e32 v57, v57, v66
	v_sub_f32_e32 v56, v56, v66
	v_sub_f32_e32 v55, v55, v66
	v_sub_f32_e32 v54, v54, v66
	v_add_f32_e32 v123, v67, v116
	v_pk_mul_f32 v[66:67], v[120:121], v[56:57] op_sel_hi:[0,1]
	v_pk_mul_f32 v[120:121], v[120:121], v[54:55] op_sel_hi:[0,1]
	ds_read_b128 v[54:57], v221 offset:528
	ds_read_b128 v[114:117], v221 offset:1552
	s_waitcnt lgkmcnt(0)
; #define LAS __attribute__((address_space(3)))
; DI unsigned pkh2(float a, float b) { typedef _Float16 h2 __attribute__((ext_vector_type(2))); h2 v; v[0] = (_Float16)a; v[1] = (_Float16)b; return __builtin_bit_cast(unsigned, v); }
;   DI void operator()(const f32x4 (&acc)[2][2][4][2], const pg8::Unit& u, int wr, int wc, int fr, int fq, LAS unsigned char* lds, int ui, int wid) const {
;     ...
;     for (int i = 0; i < 8; ++i) { typedef float f32x2_ __attribute__((ext_vector_type(2))); const f32x2_ sv = *(const LAS f32x2_*)(sl + (i >> 2) * 128 + ((i & 3) * 16 + fr_) * 2);
;       const float mu = sv.x * (1.0f / 1024.0f), var = fmaxf(sv.y * (1.0f / 1024.0f) - mu * mu, 0.f); rmu[i] = mu; rrs[i] = rsqrtf(var + 1e-5f); }
; #pragma unroll
;     for (int ai = 0; ai < 2; ++ai) {
;       half8 tpv[4][2];
; #pragma unroll
;       for (int m = 0; m < 4; ++m)
; #pragma unroll
;         for (int bj = 0; bj < 2; ++bj) tpv[m][bj] = *(const half8*)(tb + (size_t)(u.pm * 256 + ai * 128 + wr * 64 + m * 16 + fr) * DM + col0 + bj * 128);
; #pragma unroll
;       for (int m = 0; m < 4; ++m) {
;         const int row = u.pm * 256 + ai * 128 + wr * 64 + m * 16 + fr; const float mu = rmu[ai * 4 + m], rstd = rrs[ai * 4 + m];
;         float rs = 0.f, rq = 0.f;
; #pragma unroll
;         for (int bj = 0; bj < 2; ++bj) {
;           u32x4 w;
; #pragma unroll
;           for (int n = 0; n < 2; ++n) {
;             f32x4 tp;
; #pragma unroll
;             for (int j = 0; j < 4; ++j) tp[j] = (float)tpv[m][bj][4 * n + j];
;             tp = (tp - mu) * rstd * (*(const LAS f32x4*)(gl + bj * 128 + 4 * n)) + *(const LAS f32x4*)(gl + 256 + bj * 128 + 4 * n);
;             const f32x4 tn = tp * ALPHA + acc[ai][bj][m][n] * scale;
;             w[2 * n] = pkh2(tn[0], tn[1]); w[2 * n + 1] = pkh2(tn[2], tn[3]);
;             rs += tn[0] + tn[1] + tn[2] + tn[3]; rq += tn[0] * tn[0] + tn[1] * tn[1] + tn[2] * tn[2] + tn[3] * tn[3];
;           }
;           *(u32x4*)(tb + (size_t)row * DM + col0 + bj * 128) = w;
;         }
;         rs += __shfl_xor(rs, 16); rs += __shfl_xor(rs, 32); rq += __shfl_xor(rq, 16); rq += __shfl_xor(rq, 32);
;         if (fq == 0) { atomicAdd(stats_new + 2 * row, rs); atomicAdd(stats_new + 2 * row + 1, rq); }
	v_pk_fma_f32 v[66:67], v[66:67], v[54:55], v[114:115]
	v_pk_fma_f32 v[120:121], v[120:121], v[56:57], v[116:117]
	v_pk_mul_f32 v[66:67], v[66:67], s[52:53] op_sel_hi:[1,0]
	v_pk_mul_f32 v[120:121], v[120:121], s[52:53] op_sel_hi:[1,0]
	v_pk_fma_f32 v[50:51], s[12:13], v[50:51], v[66:67]
	v_pk_fma_f32 v[52:53], s[14:15], v[52:53], v[120:121]
	v_cvt_pk_f16_f32 v120, v50, v51
	v_add_f32_e32 v66, v50, v51
	v_mul_f32_e32 v51, v51, v51
	v_fmac_f32_e32 v51, v50, v50
	v_add_f32_e32 v66, v52, v66
	v_fmac_f32_e32 v51, v52, v52
	v_add_f32_e32 v66, v53, v66
	v_fmac_f32_e32 v51, v53, v53
	v_cvt_pk_f16_f32 v121, v52, v53
	v_add_f32_e32 v66, v123, v66
	v_add_f32_e32 v52, v127, v51
	v_mov_b32_e32 v50, v66
	v_mov_b32_e32 v53, v52
	global_store_dwordx4 v[136:137], v[118:121], off offset:256
	s_nop 1
	v_permlane16_swap_b32_e32 v50, v66
	v_permlane16_swap_b32_e32 v53, v52
	v_add_f32_e32 v50, v66, v50
	s_waitcnt lgkmcnt(0)
	v_add_f32_e32 v52, v52, v53
	v_mov_b32_e32 v51, v50
	v_mov_b32_e32 v53, v52
	s_nop 1
	v_permlane32_swap_b32_e32 v51, v50
	v_permlane32_swap_b32_e32 v53, v52
	s_and_saveexec_b64 s[30:31], s[6:7]
	s_cbranch_execz .LBB0_901
	v_lshlrev_b32_e32 v66, 1, v134
	v_ashrrev_i32_e32 v67, 31, v66
	v_lshl_add_u64 v[66:67], v[66:67], 2, s[16:17]
	s_waitcnt lgkmcnt(1)
	v_add_f32_e32 v50, v50, v51
	s_waitcnt lgkmcnt(0)
	v_add_f32_e32 v51, v52, v53
	global_atomic_add_f32 v[66:67], v50, off
	global_atomic_add_f32 v[66:67], v51, off offset:4
.LBB0_901:
	s_or_b64 exec, exec, s[30:31]
	s_waitcnt lgkmcnt(1)
	v_pk_mul_f32 v[50:51], v[68:69], s[44:45] op_sel_hi:[1,0]
	s_waitcnt vmcnt(7) lgkmcnt(0)
	v_cvt_f32_f16_sdwa v53, v106 dst_sel:DWORD dst_unused:UNUSED_PAD src0_sel:WORD_1
	v_fma_f32 v51, -v50, v50, v51
	v_max_f32_e32 v51, 0, v51
	v_add_f32_e32 v51, 0x3727c5ac, v51
	v_mul_f32_e32 v52, 0x4b800000, v51
	v_cmp_gt_f32_e32 vcc, s36, v51
	v_cvt_f32_f16_sdwa v66, v107 dst_sel:DWORD dst_unused:UNUSED_PAD src0_sel:WORD_1
	v_cvt_f32_f16_e32 v68, v106
	v_cndmask_b32_e32 v51, v51, v52, vcc
	v_rsq_f32_e32 v51, v51
	v_sub_f32_e32 v67, v66, v50
	v_sub_f32_e32 v69, v53, v50
	v_sub_f32_e32 v68, v68, v50
	v_mul_f32_e32 v52, 0x45800000, v51
	v_cndmask_b32_e32 v52, v51, v52, vcc
	v_cvt_f32_f16_e32 v51, v107
	v_pk_mul_f32 v[68:69], v[52:53], v[68:69] op_sel_hi:[0,1]
	v_pk_fma_f32 v[68:69], v[90:91], v[68:69], v[94:95]
	v_sub_f32_e32 v66, v51, v50
	v_pk_mul_f32 v[66:67], v[52:53], v[66:67] op_sel_hi:[0,1]
	v_pk_fma_f32 v[66:67], v[92:93], v[66:67], v[96:97]
	v_pk_mul_f32 v[68:69], v[68:69], s[52:53] op_sel_hi:[1,0]
	v_pk_mul_f32 v[66:67], v[66:67], s[52:53] op_sel_hi:[1,0]
	s_nop 0
	v_pk_fma_f32 v[48:49], s[14:15], v[48:49], v[66:67]
	v_pk_fma_f32 v[66:67], s[12:13], v[46:47], v[68:69]
	v_cvt_f32_f16_e32 v69, v108
	v_mul_f32_e32 v53, v67, v67
	v_cvt_pk_f16_f32 v46, v66, v67
	v_add_f32_e32 v51, v66, v67
	v_fmac_f32_e32 v53, v66, v66
	v_cvt_f32_f16_sdwa v66, v108 dst_sel:DWORD dst_unused:UNUSED_PAD src0_sel:WORD_1
	v_cvt_pk_f16_f32 v47, v48, v49
	v_add_f32_e32 v51, v48, v51
	v_fmac_f32_e32 v53, v48, v48
	v_cvt_f32_f16_sdwa v48, v109 dst_sel:DWORD dst_unused:UNUSED_PAD src0_sel:WORD_1
	v_cvt_f32_f16_e32 v68, v109
	v_fmac_f32_e32 v53, v49, v49
	v_sub_f32_e32 v67, v66, v50
	v_sub_f32_e32 v66, v69, v50
	v_add_f32_e32 v51, v49, v51
	v_sub_f32_e32 v49, v48, v50
	v_sub_f32_e32 v48, v68, v50
	v_pk_mul_f32 v[66:67], v[52:53], v[66:67] op_sel_hi:[0,1]
	v_pk_mul_f32 v[48:49], v[52:53], v[48:49] op_sel_hi:[0,1]
	v_pk_fma_f32 v[66:67], v[66:67], v[82:83], v[70:71]
	v_pk_fma_f32 v[48:49], v[48:49], v[84:85], v[72:73]
	v_pk_mul_f32 v[66:67], v[66:67], s[52:53] op_sel_hi:[1,0]
	v_pk_mul_f32 v[48:49], v[48:49], s[52:53] op_sel_hi:[1,0]
	v_pk_fma_f32 v[42:43], s[12:13], v[42:43], v[66:67]
	v_pk_fma_f32 v[44:45], s[14:15], v[44:45], v[48:49]
	v_add_f32_e32 v66, v42, v43
	v_add_f32_e32 v66, v44, v66
	v_add_f32_e32 v51, 0, v51
	v_cvt_pk_f16_f32 v48, v42, v43
	v_add_f32_e32 v66, v45, v66
	v_mul_f32_e32 v43, v43, v43
	v_add_f32_e32 v51, v66, v51
	v_fmac_f32_e32 v43, v42, v42
	s_waitcnt vmcnt(6)
	v_cvt_f32_f16_sdwa v66, v102 dst_sel:DWORD dst_unused:UNUSED_PAD src0_sel:WORD_1
	v_cvt_f32_f16_e32 v69, v102
	v_cvt_pk_f16_f32 v49, v44, v45
	v_fmac_f32_e32 v43, v44, v44
	v_cvt_f32_f16_sdwa v44, v103 dst_sel:DWORD dst_unused:UNUSED_PAD src0_sel:WORD_1
	v_cvt_f32_f16_e32 v68, v103
	v_fmac_f32_e32 v43, v45, v45
	v_add_f32_e32 v53, v53, v43
	v_sub_f32_e32 v67, v66, v50
	v_sub_f32_e32 v66, v69, v50
	v_sub_f32_e32 v45, v44, v50
	v_sub_f32_e32 v44, v68, v50
	v_pk_mul_f32 v[66:67], v[52:53], v[66:67] op_sel_hi:[0,1]
	v_pk_mul_f32 v[44:45], v[52:53], v[44:45] op_sel_hi:[0,1]
	v_pk_fma_f32 v[66:67], v[66:67], v[62:63], v[110:111]
	v_pk_fma_f32 v[44:45], v[44:45], v[64:65], v[112:113]
	v_pk_mul_f32 v[66:67], v[66:67], s[52:53] op_sel_hi:[1,0]
	v_pk_mul_f32 v[44:45], v[44:45], s[52:53] op_sel_hi:[1,0]
	v_pk_fma_f32 v[38:39], s[12:13], v[38:39], v[66:67]
	v_pk_fma_f32 v[40:41], s[14:15], v[40:41], v[44:45]
	v_add_f32_e32 v44, v38, v39
	v_add_f32_e32 v44, v40, v44
	v_add_f32_e32 v44, v41, v44
	v_add_f32_e32 v66, v51, v44
	v_mul_f32_e32 v44, v39, v39
	v_fmac_f32_e32 v44, v38, v38
	v_fmac_f32_e32 v44, v40, v40
	v_fmac_f32_e32 v44, v41, v41
	v_add_f32_e32 v53, v53, v44
	v_cvt_f32_f16_sdwa v44, v105 dst_sel:DWORD dst_unused:UNUSED_PAD src0_sel:WORD_1
	v_cvt_f32_f16_sdwa v51, v104 dst_sel:DWORD dst_unused:UNUSED_PAD src0_sel:WORD_1
	v_cvt_f32_f16_e32 v67, v105
	v_cvt_f32_f16_e32 v68, v104
	v_sub_f32_e32 v45, v44, v50
	v_sub_f32_e32 v51, v51, v50
	v_sub_f32_e32 v44, v67, v50
	v_sub_f32_e32 v50, v68, v50
	v_pk_mul_f32 v[50:51], v[52:53], v[50:51] op_sel_hi:[0,1]
	v_pk_fma_f32 v[50:51], v[50:51], v[54:55], v[114:115]
	v_pk_mul_f32 v[44:45], v[52:53], v[44:45] op_sel_hi:[0,1]
	v_pk_mul_f32 v[50:51], v[50:51], s[52:53] op_sel_hi:[1,0]
	v_pk_fma_f32 v[44:45], v[44:45], v[56:57], v[116:117]
	v_pk_fma_f32 v[50:51], s[12:13], v[34:35], v[50:51]
	v_pk_mul_f32 v[44:45], v[44:45], s[52:53] op_sel_hi:[1,0]
	v_mul_f32_e32 v35, v51, v51
	v_pk_fma_f32 v[44:45], s[14:15], v[36:37], v[44:45]
	v_add_f32_e32 v34, v50, v51
	v_fmac_f32_e32 v35, v50, v50
	v_add_f32_e32 v34, v44, v34
	v_fmac_f32_e32 v35, v44, v44
	v_add_f32_e32 v34, v45, v34
	v_fmac_f32_e32 v35, v45, v45
	v_add_f32_e32 v34, v66, v34
	v_add_f32_e32 v37, v53, v35
	v_mov_b32_e32 v36, v34
	v_mov_b32_e32 v52, v37
	v_lshl_add_u64 v[42:43], s[76:77], 0, v[132:133]
	v_lshl_add_u64 v[42:43], v[210:211], 1, v[42:43]
	v_cvt_pk_f16_f32 v38, v38, v39
	s_nop 1
	v_permlane16_swap_b32_e32 v36, v34
	v_permlane16_swap_b32_e32 v52, v37
	v_add_f32_e32 v34, v34, v36
	s_waitcnt lgkmcnt(0)
	v_add_f32_e32 v36, v37, v52
	v_mov_b32_e32 v35, v34
	v_mov_b32_e32 v37, v36
	s_nop 1
	v_permlane32_swap_b32_e32 v35, v34
	v_permlane32_swap_b32_e32 v37, v36
	v_cvt_pk_f16_f32 v39, v40, v41
	v_cvt_pk_f16_f32 v40, v50, v51
	v_cvt_pk_f16_f32 v41, v44, v45
	global_store_dwordx4 v[42:43], v[46:49], off
	global_store_dwordx4 v[42:43], v[38:41], off offset:256
	s_and_saveexec_b64 s[30:31], s[6:7]
	s_cbranch_execz .LBB0_903
; #define LAS __attribute__((address_space(3)))
; DI unsigned pkh2(float a, float b) { typedef _Float16 h2 __attribute__((ext_vector_type(2))); h2 v; v[0] = (_Float16)a; v[1] = (_Float16)b; return __builtin_bit_cast(unsigned, v); }
;   DI void operator()(const f32x4 (&acc)[2][2][4][2], const pg8::Unit& u, int wr, int wc, int fr, int fq, LAS unsigned char* lds, int ui, int wid) const {
;     ...
;     for (int i = 0; i < 8; ++i) { typedef float f32x2_ __attribute__((ext_vector_type(2))); const f32x2_ sv = *(const LAS f32x2_*)(sl + (i >> 2) * 128 + ((i & 3) * 16 + fr_) * 2);
;       const float mu = sv.x * (1.0f / 1024.0f), var = fmaxf(sv.y * (1.0f / 1024.0f) - mu * mu, 0.f); rmu[i] = mu; rrs[i] = rsqrtf(var + 1e-5f); }
; #pragma unroll
;     for (int ai = 0; ai < 2; ++ai) {
;       half8 tpv[4][2];
; #pragma unroll
;       for (int m = 0; m < 4; ++m)
; #pragma unroll
;         for (int bj = 0; bj < 2; ++bj) tpv[m][bj] = *(const half8*)(tb + (size_t)(u.pm * 256 + ai * 128 + wr * 64 + m * 16 + fr) * DM + col0 + bj * 128);
; #pragma unroll
;       for (int m = 0; m < 4; ++m) {
;         const int row = u.pm * 256 + ai * 128 + wr * 64 + m * 16 + fr; const float mu = rmu[ai * 4 + m], rstd = rrs[ai * 4 + m];
;         float rs = 0.f, rq = 0.f;
; #pragma unroll
;         for (int bj = 0; bj < 2; ++bj) {
;           u32x4 w;
; #pragma unroll
;           for (int n = 0; n < 2; ++n) {
;             f32x4 tp;
; #pragma unroll
;             for (int j = 0; j < 4; ++j) tp[j] = (float)tpv[m][bj][4 * n + j];
;             tp = (tp - mu) * rstd * (*(const LAS f32x4*)(gl + bj * 128 + 4 * n)) + *(const LAS f32x4*)(gl + 256 + bj * 128 + 4 * n);
;             const f32x4 tn = tp * ALPHA + acc[ai][bj][m][n] * scale;
;             w[2 * n] = pkh2(tn[0], tn[1]); w[2 * n + 1] = pkh2(tn[2], tn[3]);
;             rs += tn[0] + tn[1] + tn[2] + tn[3]; rq += tn[0] * tn[0] + tn[1] * tn[1] + tn[2] * tn[2] + tn[3] * tn[3];
;           }
;           *(u32x4*)(tb + (size_t)row * DM + col0 + bj * 128) = w;
;         }
;         rs += __shfl_xor(rs, 16); rs += __shfl_xor(rs, 32); rq += __shfl_xor(rq, 16); rq += __shfl_xor(rq, 32);
;         if (fq == 0) { atomicAdd(stats_new + 2 * row, rs); atomicAdd(stats_new + 2 * row + 1, rq); }
	v_lshlrev_b32_e32 v38, 1, v130
	v_ashrrev_i32_e32 v39, 31, v38
	v_lshl_add_u64 v[38:39], v[38:39], 2, s[16:17]
	s_waitcnt lgkmcnt(1)
	v_add_f32_e32 v34, v34, v35
	s_waitcnt lgkmcnt(0)
	v_add_f32_e32 v35, v36, v37
	global_atomic_add_f32 v[38:39], v34, off
	global_atomic_add_f32 v[38:39], v35, off offset:4
.LBB0_903:
	s_or_b64 exec, exec, s[30:31]
	s_waitcnt lgkmcnt(1)
	v_pk_mul_f32 v[34:35], v[58:59], s[44:45] op_sel_hi:[1,0]
	s_waitcnt vmcnt(7) lgkmcnt(0)
	v_cvt_f32_f16_sdwa v37, v98 dst_sel:DWORD dst_unused:UNUSED_PAD src0_sel:WORD_1
	v_fma_f32 v35, -v34, v34, v35
	v_max_f32_e32 v35, 0, v35
	v_add_f32_e32 v35, 0x3727c5ac, v35
	v_mul_f32_e32 v36, 0x4b800000, v35
	v_cmp_gt_f32_e32 vcc, s36, v35
	v_cvt_f32_f16_sdwa v38, v99 dst_sel:DWORD dst_unused:UNUSED_PAD src0_sel:WORD_1
	v_cvt_f32_f16_e32 v40, v98
	v_cndmask_b32_e32 v35, v35, v36, vcc
	v_rsq_f32_e32 v35, v35
	v_sub_f32_e32 v39, v38, v34
	v_sub_f32_e32 v41, v37, v34
	v_sub_f32_e32 v40, v40, v34
	v_mul_f32_e32 v36, 0x45800000, v35
	v_cndmask_b32_e32 v36, v35, v36, vcc
	v_cvt_f32_f16_e32 v35, v99
	v_pk_mul_f32 v[40:41], v[36:37], v[40:41] op_sel_hi:[0,1]
	v_pk_fma_f32 v[40:41], v[90:91], v[40:41], v[94:95]
	v_sub_f32_e32 v38, v35, v34
	v_pk_mul_f32 v[38:39], v[36:37], v[38:39] op_sel_hi:[0,1]
	v_pk_fma_f32 v[38:39], v[92:93], v[38:39], v[96:97]
	v_pk_mul_f32 v[40:41], v[40:41], s[52:53] op_sel_hi:[1,0]
	v_pk_mul_f32 v[38:39], v[38:39], s[52:53] op_sel_hi:[1,0]
	s_nop 0
	v_pk_fma_f32 v[30:31], s[14:15], v[30:31], v[38:39]
	v_pk_fma_f32 v[38:39], s[12:13], v[28:29], v[40:41]
	v_cvt_f32_f16_e32 v41, v100
	v_mul_f32_e32 v37, v39, v39
	v_cvt_pk_f16_f32 v28, v38, v39
	v_add_f32_e32 v35, v38, v39
	v_fmac_f32_e32 v37, v38, v38
	v_cvt_f32_f16_sdwa v38, v100 dst_sel:DWORD dst_unused:UNUSED_PAD src0_sel:WORD_1
	v_cvt_pk_f16_f32 v29, v30, v31
	v_add_f32_e32 v35, v30, v35
	v_fmac_f32_e32 v37, v30, v30
	v_cvt_f32_f16_sdwa v30, v101 dst_sel:DWORD dst_unused:UNUSED_PAD src0_sel:WORD_1
	v_cvt_f32_f16_e32 v40, v101
	v_fmac_f32_e32 v37, v31, v31
	v_sub_f32_e32 v39, v38, v34
	v_sub_f32_e32 v38, v41, v34
	v_add_f32_e32 v35, v31, v35
	v_sub_f32_e32 v31, v30, v34
	v_sub_f32_e32 v30, v40, v34
	v_pk_mul_f32 v[38:39], v[36:37], v[38:39] op_sel_hi:[0,1]
	v_pk_mul_f32 v[30:31], v[36:37], v[30:31] op_sel_hi:[0,1]
	v_pk_fma_f32 v[38:39], v[82:83], v[38:39], v[70:71]
	v_pk_fma_f32 v[30:31], v[84:85], v[30:31], v[72:73]
	v_pk_mul_f32 v[38:39], v[38:39], s[52:53] op_sel_hi:[1,0]
	v_pk_mul_f32 v[30:31], v[30:31], s[52:53] op_sel_hi:[1,0]
	v_pk_fma_f32 v[24:25], s[12:13], v[24:25], v[38:39]
	v_pk_fma_f32 v[26:27], s[14:15], v[26:27], v[30:31]
	v_add_f32_e32 v38, v24, v25
	v_add_f32_e32 v38, v26, v38
	v_add_f32_e32 v35, 0, v35
	v_cvt_pk_f16_f32 v30, v24, v25
	v_add_f32_e32 v38, v27, v38
	v_mul_f32_e32 v25, v25, v25
	v_add_f32_e32 v35, v38, v35
	v_fmac_f32_e32 v25, v24, v24
	s_waitcnt vmcnt(6)
	v_cvt_f32_f16_sdwa v38, v86 dst_sel:DWORD dst_unused:UNUSED_PAD src0_sel:WORD_1
	v_cvt_f32_f16_e32 v41, v86
	v_cvt_pk_f16_f32 v31, v26, v27
	v_fmac_f32_e32 v25, v26, v26
	v_cvt_f32_f16_sdwa v26, v87 dst_sel:DWORD dst_unused:UNUSED_PAD src0_sel:WORD_1
	v_cvt_f32_f16_e32 v40, v87
	v_fmac_f32_e32 v25, v27, v27
	v_add_f32_e32 v37, v37, v25
	v_sub_f32_e32 v39, v38, v34
	v_sub_f32_e32 v38, v41, v34
	v_sub_f32_e32 v27, v26, v34
	v_sub_f32_e32 v26, v40, v34
	v_pk_mul_f32 v[38:39], v[36:37], v[38:39] op_sel_hi:[0,1]
	v_pk_mul_f32 v[26:27], v[36:37], v[26:27] op_sel_hi:[0,1]
	v_pk_fma_f32 v[38:39], v[38:39], v[62:63], v[110:111]
	v_pk_fma_f32 v[26:27], v[26:27], v[64:65], v[112:113]
	v_pk_mul_f32 v[38:39], v[38:39], s[52:53] op_sel_hi:[1,0]
	v_pk_mul_f32 v[26:27], v[26:27], s[52:53] op_sel_hi:[1,0]
	v_pk_fma_f32 v[20:21], s[12:13], v[20:21], v[38:39]
	v_pk_fma_f32 v[22:23], s[14:15], v[22:23], v[26:27]
	v_add_f32_e32 v26, v20, v21
	v_add_f32_e32 v26, v22, v26
	v_add_f32_e32 v26, v23, v26
	v_add_f32_e32 v38, v26, v35
	v_mul_f32_e32 v26, v21, v21
	v_fmac_f32_e32 v26, v20, v20
	v_fmac_f32_e32 v26, v22, v22
	v_fmac_f32_e32 v26, v23, v23
	v_add_f32_e32 v37, v37, v26
	v_cvt_f32_f16_sdwa v26, v89 dst_sel:DWORD dst_unused:UNUSED_PAD src0_sel:WORD_1
	v_cvt_f32_f16_sdwa v35, v88 dst_sel:DWORD dst_unused:UNUSED_PAD src0_sel:WORD_1
	v_cvt_f32_f16_e32 v39, v89
	v_cvt_f32_f16_e32 v40, v88
	v_sub_f32_e32 v27, v26, v34
	v_sub_f32_e32 v35, v35, v34
	v_sub_f32_e32 v26, v39, v34
	v_sub_f32_e32 v34, v40, v34
	v_pk_mul_f32 v[34:35], v[36:37], v[34:35] op_sel_hi:[0,1]
	v_pk_fma_f32 v[34:35], v[34:35], v[54:55], v[114:115]
	v_pk_mul_f32 v[26:27], v[36:37], v[26:27] op_sel_hi:[0,1]
	v_pk_mul_f32 v[34:35], v[34:35], s[52:53] op_sel_hi:[1,0]
	v_pk_fma_f32 v[26:27], v[26:27], v[56:57], v[116:117]
	v_pk_fma_f32 v[34:35], s[12:13], v[16:17], v[34:35]
	v_pk_mul_f32 v[26:27], v[26:27], s[52:53] op_sel_hi:[1,0]
	v_mul_f32_e32 v17, v35, v35
	v_pk_fma_f32 v[26:27], s[14:15], v[18:19], v[26:27]
	v_add_f32_e32 v16, v34, v35
	v_fmac_f32_e32 v17, v34, v34
	v_add_f32_e32 v16, v26, v16
	v_fmac_f32_e32 v17, v26, v26
	v_add_f32_e32 v16, v27, v16
	v_fmac_f32_e32 v17, v27, v27
	v_add_f32_e32 v16, v38, v16
	v_add_f32_e32 v19, v37, v17
	v_mov_b32_e32 v18, v16
	v_mov_b32_e32 v36, v19
	v_lshl_add_u64 v[24:25], s[76:77], 0, v[128:129]
	v_lshl_add_u64 v[24:25], v[210:211], 1, v[24:25]
	v_cvt_pk_f16_f32 v20, v20, v21
	s_nop 1
	v_permlane16_swap_b32_e32 v18, v16
	v_permlane16_swap_b32_e32 v36, v19
	v_add_f32_e32 v16, v16, v18
	s_waitcnt lgkmcnt(0)
	v_add_f32_e32 v18, v19, v36
	v_mov_b32_e32 v17, v16
	v_mov_b32_e32 v19, v18
	s_nop 1
	v_permlane32_swap_b32_e32 v17, v16
	v_permlane32_swap_b32_e32 v19, v18
	v_cvt_pk_f16_f32 v21, v22, v23
	v_cvt_pk_f16_f32 v22, v34, v35
	v_cvt_pk_f16_f32 v23, v26, v27
	global_store_dwordx4 v[24:25], v[28:31], off
	global_store_dwordx4 v[24:25], v[20:23], off offset:256
	s_and_saveexec_b64 s[30:31], s[6:7]
	s_cbranch_execz .LBB0_905
	v_lshlrev_b32_e32 v20, 1, v126
	v_ashrrev_i32_e32 v21, 31, v20
	v_lshl_add_u64 v[20:21], v[20:21], 2, s[16:17]
	s_waitcnt lgkmcnt(1)
	v_add_f32_e32 v16, v16, v17
	s_waitcnt lgkmcnt(0)
	v_add_f32_e32 v17, v18, v19
	global_atomic_add_f32 v[20:21], v16, off
	global_atomic_add_f32 v[20:21], v17, off offset:4
; #define LAS __attribute__((address_space(3)))
; DI unsigned pkh2(float a, float b) { typedef _Float16 h2 __attribute__((ext_vector_type(2))); h2 v; v[0] = (_Float16)a; v[1] = (_Float16)b; return __builtin_bit_cast(unsigned, v); }
;   DI void operator()(const f32x4 (&acc)[2][2][4][2], const pg8::Unit& u, int wr, int wc, int fr, int fq, LAS unsigned char* lds, int ui, int wid) const {
;     ...
;     for (int i = 0; i < 8; ++i) { typedef float f32x2_ __attribute__((ext_vector_type(2))); const f32x2_ sv = *(const LAS f32x2_*)(sl + (i >> 2) * 128 + ((i & 3) * 16 + fr_) * 2);
;       const float mu = sv.x * (1.0f / 1024.0f), var = fmaxf(sv.y * (1.0f / 1024.0f) - mu * mu, 0.f); rmu[i] = mu; rrs[i] = rsqrtf(var + 1e-5f); }
; #pragma unroll
;     for (int ai = 0; ai < 2; ++ai) {
;       half8 tpv[4][2];
; #pragma unroll
;       for (int m = 0; m < 4; ++m)
; #pragma unroll
;         for (int bj = 0; bj < 2; ++bj) tpv[m][bj] = *(const half8*)(tb + (size_t)(u.pm * 256 + ai * 128 + wr * 64 + m * 16 + fr) * DM + col0 + bj * 128);
; #pragma unroll
;       for (int m = 0; m < 4; ++m) {
;         const int row = u.pm * 256 + ai * 128 + wr * 64 + m * 16 + fr; const float mu = rmu[ai * 4 + m], rstd = rrs[ai * 4 + m];
;         float rs = 0.f, rq = 0.f;
; #pragma unroll
;         for (int bj = 0; bj < 2; ++bj) {
;           u32x4 w;
; #pragma unroll
;           for (int n = 0; n < 2; ++n) {
;             f32x4 tp;
; #pragma unroll
;             for (int j = 0; j < 4; ++j) tp[j] = (float)tpv[m][bj][4 * n + j];
;             tp = (tp - mu) * rstd * (*(const LAS f32x4*)(gl + bj * 128 + 4 * n)) + *(const LAS f32x4*)(gl + 256 + bj * 128 + 4 * n);
;             const f32x4 tn = tp * ALPHA + acc[ai][bj][m][n] * scale;
;             w[2 * n] = pkh2(tn[0], tn[1]); w[2 * n + 1] = pkh2(tn[2], tn[3]);
;             rs += tn[0] + tn[1] + tn[2] + tn[3]; rq += tn[0] * tn[0] + tn[1] * tn[1] + tn[2] * tn[2] + tn[3] * tn[3];
;           }
;           *(u32x4*)(tb + (size_t)row * DM + col0 + bj * 128) = w;
;         }
;         rs += __shfl_xor(rs, 16); rs += __shfl_xor(rs, 32); rq += __shfl_xor(rq, 16); rq += __shfl_xor(rq, 32);
;         if (fq == 0) { atomicAdd(stats_new + 2 * row, rs); atomicAdd(stats_new + 2 * row + 1, rq); }
.LBB0_905:
	s_or_b64 exec, exec, s[30:31]
	s_waitcnt lgkmcnt(1)
	v_pk_mul_f32 v[16:17], v[60:61], s[44:45] op_sel_hi:[1,0]
	s_waitcnt vmcnt(7) lgkmcnt(0)
	v_cvt_f32_f16_sdwa v19, v78 dst_sel:DWORD dst_unused:UNUSED_PAD src0_sel:WORD_1
	v_fma_f32 v17, -v16, v16, v17
	v_max_f32_e32 v17, 0, v17
	v_add_f32_e32 v17, 0x3727c5ac, v17
	v_mul_f32_e32 v18, 0x4b800000, v17
	v_cmp_gt_f32_e32 vcc, s36, v17
	v_cvt_f32_f16_sdwa v20, v79 dst_sel:DWORD dst_unused:UNUSED_PAD src0_sel:WORD_1
	v_cvt_f32_f16_e32 v22, v78
	v_cndmask_b32_e32 v17, v17, v18, vcc
	v_rsq_f32_e32 v17, v17
	v_sub_f32_e32 v21, v20, v16
	v_sub_f32_e32 v23, v19, v16
	v_sub_f32_e32 v22, v22, v16
	v_mul_f32_e32 v18, 0x45800000, v17
	v_cndmask_b32_e32 v18, v17, v18, vcc
	v_cvt_f32_f16_e32 v17, v79
	v_pk_mul_f32 v[22:23], v[18:19], v[22:23] op_sel_hi:[0,1]
	v_pk_fma_f32 v[22:23], v[90:91], v[22:23], v[94:95]
	v_sub_f32_e32 v20, v17, v16
	v_pk_mul_f32 v[20:21], v[18:19], v[20:21] op_sel_hi:[0,1]
	v_pk_fma_f32 v[20:21], v[92:93], v[20:21], v[96:97]
	v_pk_mul_f32 v[22:23], v[22:23], s[52:53] op_sel_hi:[1,0]
	v_pk_mul_f32 v[20:21], v[20:21], s[52:53] op_sel_hi:[1,0]
	s_nop 0
	v_pk_fma_f32 v[14:15], s[14:15], v[14:15], v[20:21]
	v_pk_fma_f32 v[20:21], s[12:13], v[12:13], v[22:23]
	v_cvt_f32_f16_e32 v23, v80
	v_mul_f32_e32 v19, v21, v21
	v_cvt_pk_f16_f32 v12, v20, v21
	v_add_f32_e32 v17, v20, v21
	v_fmac_f32_e32 v19, v20, v20
	v_cvt_f32_f16_sdwa v20, v80 dst_sel:DWORD dst_unused:UNUSED_PAD src0_sel:WORD_1
	v_cvt_pk_f16_f32 v13, v14, v15
	v_add_f32_e32 v17, v14, v17
	v_fmac_f32_e32 v19, v14, v14
	v_cvt_f32_f16_sdwa v14, v81 dst_sel:DWORD dst_unused:UNUSED_PAD src0_sel:WORD_1
	v_cvt_f32_f16_e32 v22, v81
	v_fmac_f32_e32 v19, v15, v15
	v_sub_f32_e32 v21, v20, v16
	v_sub_f32_e32 v20, v23, v16
	v_add_f32_e32 v17, v15, v17
	v_sub_f32_e32 v15, v14, v16
	v_sub_f32_e32 v14, v22, v16
	v_pk_mul_f32 v[20:21], v[18:19], v[20:21] op_sel_hi:[0,1]
	v_pk_mul_f32 v[14:15], v[18:19], v[14:15] op_sel_hi:[0,1]
	v_pk_fma_f32 v[20:21], v[82:83], v[20:21], v[70:71]
	v_pk_fma_f32 v[14:15], v[84:85], v[14:15], v[72:73]
	v_pk_mul_f32 v[20:21], v[20:21], s[52:53] op_sel_hi:[1,0]
	v_pk_mul_f32 v[14:15], v[14:15], s[52:53] op_sel_hi:[1,0]
	v_pk_fma_f32 v[8:9], s[12:13], v[8:9], v[20:21]
	v_pk_fma_f32 v[10:11], s[14:15], v[10:11], v[14:15]
	v_add_f32_e32 v20, v8, v9
	v_add_f32_e32 v20, v10, v20
	v_add_f32_e32 v17, 0, v17
	v_cvt_pk_f16_f32 v14, v8, v9
	v_add_f32_e32 v20, v11, v20
	v_mul_f32_e32 v9, v9, v9
	v_add_f32_e32 v17, v20, v17
	v_fmac_f32_e32 v9, v8, v8
	s_waitcnt vmcnt(6)
	v_cvt_f32_f16_sdwa v20, v74 dst_sel:DWORD dst_unused:UNUSED_PAD src0_sel:WORD_1
	v_cvt_f32_f16_e32 v23, v74
	v_cvt_pk_f16_f32 v15, v10, v11
	v_fmac_f32_e32 v9, v10, v10
	v_cvt_f32_f16_sdwa v10, v75 dst_sel:DWORD dst_unused:UNUSED_PAD src0_sel:WORD_1
	v_cvt_f32_f16_e32 v22, v75
	v_fmac_f32_e32 v9, v11, v11
	v_add_f32_e32 v19, v19, v9
	v_sub_f32_e32 v21, v20, v16
	v_sub_f32_e32 v20, v23, v16
	v_sub_f32_e32 v11, v10, v16
	v_sub_f32_e32 v10, v22, v16
	v_pk_mul_f32 v[20:21], v[18:19], v[20:21] op_sel_hi:[0,1]
	v_pk_mul_f32 v[10:11], v[18:19], v[10:11] op_sel_hi:[0,1]
	v_pk_fma_f32 v[20:21], v[62:63], v[20:21], v[110:111]
	v_pk_fma_f32 v[10:11], v[64:65], v[10:11], v[112:113]
	v_pk_mul_f32 v[20:21], v[20:21], s[52:53] op_sel_hi:[1,0]
	v_pk_mul_f32 v[10:11], v[10:11], s[52:53] op_sel_hi:[1,0]
	v_pk_fma_f32 v[4:5], s[12:13], v[4:5], v[20:21]
	v_pk_fma_f32 v[6:7], s[14:15], v[6:7], v[10:11]
	v_add_f32_e32 v10, v4, v5
	v_add_f32_e32 v10, v6, v10
	v_add_f32_e32 v10, v7, v10
	v_add_f32_e32 v20, v10, v17
	v_mul_f32_e32 v10, v5, v5
	v_fmac_f32_e32 v10, v4, v4
	v_fmac_f32_e32 v10, v6, v6
	v_fmac_f32_e32 v10, v7, v7
	v_add_f32_e32 v19, v19, v10
	v_cvt_f32_f16_sdwa v10, v77 dst_sel:DWORD dst_unused:UNUSED_PAD src0_sel:WORD_1
	v_cvt_f32_f16_sdwa v17, v76 dst_sel:DWORD dst_unused:UNUSED_PAD src0_sel:WORD_1
	v_cvt_f32_f16_e32 v21, v77
	v_cvt_f32_f16_e32 v22, v76
	v_sub_f32_e32 v11, v10, v16
	v_sub_f32_e32 v17, v17, v16
	v_sub_f32_e32 v10, v21, v16
	v_sub_f32_e32 v16, v22, v16
	v_pk_mul_f32 v[16:17], v[18:19], v[16:17] op_sel_hi:[0,1]
	v_pk_fma_f32 v[16:17], v[16:17], v[54:55], v[114:115]
	v_pk_mul_f32 v[10:11], v[18:19], v[10:11] op_sel_hi:[0,1]
	v_pk_mul_f32 v[16:17], v[16:17], s[52:53] op_sel_hi:[1,0]
	v_pk_fma_f32 v[10:11], v[10:11], v[56:57], v[116:117]
	v_pk_fma_f32 v[16:17], s[12:13], v[0:1], v[16:17]
	v_pk_mul_f32 v[10:11], v[10:11], s[52:53] op_sel_hi:[1,0]
	v_mul_f32_e32 v1, v17, v17
	v_pk_fma_f32 v[10:11], s[14:15], v[2:3], v[10:11]
	v_add_f32_e32 v0, v16, v17
	v_fmac_f32_e32 v1, v16, v16
	v_add_f32_e32 v0, v10, v0
	v_fmac_f32_e32 v1, v10, v10
	v_add_f32_e32 v0, v11, v0
	v_fmac_f32_e32 v1, v11, v11
	v_add_f32_e32 v0, v0, v20
	v_add_f32_e32 v3, v1, v19
	v_mov_b32_e32 v2, v0
	v_mov_b32_e32 v18, v3
	v_lshl_add_u64 v[8:9], s[76:77], 0, v[124:125]
	v_lshl_add_u64 v[8:9], v[210:211], 1, v[8:9]
	v_cvt_pk_f16_f32 v4, v4, v5
	s_nop 1
	v_permlane16_swap_b32_e32 v2, v0
	v_permlane16_swap_b32_e32 v18, v3
	v_add_f32_e32 v0, v0, v2
	s_waitcnt lgkmcnt(0)
	v_add_f32_e32 v2, v3, v18
	v_mov_b32_e32 v1, v0
	v_mov_b32_e32 v3, v2
	s_nop 1
	v_permlane32_swap_b32_e32 v1, v0
	v_permlane32_swap_b32_e32 v3, v2
	v_cvt_pk_f16_f32 v5, v6, v7
	v_cvt_pk_f16_f32 v6, v16, v17
	v_cvt_pk_f16_f32 v7, v10, v11
	global_store_dwordx4 v[8:9], v[12:15], off
	global_store_dwordx4 v[8:9], v[4:7], off offset:256
	s_and_saveexec_b64 s[30:31], s[6:7]
	s_cbranch_execz .LBB0_907
	v_lshlrev_b32_e32 v4, 1, v122
	v_ashrrev_i32_e32 v5, 31, v4
	v_lshl_add_u64 v[4:5], v[4:5], 2, s[16:17]
	s_waitcnt lgkmcnt(1)
	v_add_f32_e32 v0, v0, v1
	s_waitcnt lgkmcnt(0)
	v_add_f32_e32 v1, v2, v3
	global_atomic_add_f32 v[4:5], v0, off
	global_atomic_add_f32 v[4:5], v1, off offset:4
